# stack15 plus write-through sc0 sc1 on the converted bf16 weight stores
# baseline (speedup 1.0000x reference)
; #define LAS __attribute__((address_space(3)))
; __device__ __forceinline__ void transpose_item(const float* W, int K, int N, bf16* WT, int k0, int n0, int dst_row0, LAS float* scr, int lane) {
;     float wv[32];
; #pragma unroll
;     for (int i = 0; i < 32; ++i) wv[i] = __builtin_nontemporal_load(W + (size_t)(k0 + 2 * i + (lane >> 5)) * N + n0 + (lane & 31));
; __device__ __forceinline__ void convert_weights(const Args& A, int l, LAS unsigned char* lds, int gw, int ngw, int wave, int lane) {
;     ...
;         if (r < I_IN) { const int kb = r / 168, nb = r % 168, n0 = nb * 32;
;             bf16* dst; int drow;
;             if (n0 < 1024) { dst = WB + WO_W1M; drow = n0; }
;             else if (n0 < 1536) { dst = WB + WO_W1S; drow = n0 - 1024; }
;             else if (n0 < 2048) { dst = WB + WO_W1M; drow = n0 - 512; }
;             else if (n0 < 2304) { dst = WB + WO_W1S; drow = n0 - 1536; }
;             else { dst = WB + WO_W1M; const int gcol = n0 - 2304, br = gcol >> 10, ch = gcol & 1023;
;                    drow = br == 2 ? 1536 + 2048 + ch : 1536 + (ch >> 7) * 256 + br * 128 + (ch & 127); }
.LBB0_54:
	s_lshl_b32 s20, s15, 6
	v_or_b32_e32 v58, s20, v26
	s_ashr_i32 s15, s14, 31
	v_lshl_add_u64 v[40:41], s[14:15], 2, v[24:25]
	s_movk_i32 s16, 0x5400
	v_or_b32_e32 v44, 2, v58
	v_or_b32_e32 v46, 4, v58
	v_or_b32_e32 v48, 6, v58
	v_or_b32_e32 v50, 8, v58
	v_or_b32_e32 v52, 10, v58
	v_or_b32_e32 v54, 12, v58
	v_or_b32_e32 v56, 14, v58
	v_mad_i64_i32 v[42:43], s[14:15], v58, s16, v[40:41]
	v_mad_i64_i32 v[44:45], s[14:15], v44, s16, v[40:41]
	v_mad_i64_i32 v[46:47], s[14:15], v46, s16, v[40:41]
	v_mad_i64_i32 v[48:49], s[14:15], v48, s16, v[40:41]
	v_mad_i64_i32 v[50:51], s[14:15], v50, s16, v[40:41]
	v_mad_i64_i32 v[52:53], s[14:15], v52, s16, v[40:41]
	v_mad_i64_i32 v[54:55], s[14:15], v54, s16, v[40:41]
	v_mad_i64_i32 v[56:57], s[14:15], v56, s16, v[40:41]
	global_load_dword v59, v[42:43], off nt
	global_load_dword v60, v[44:45], off nt
	global_load_dword v61, v[46:47], off nt
	global_load_dword v62, v[48:49], off nt
	global_load_dword v63, v[50:51], off nt
	global_load_dword v64, v[52:53], off nt
	global_load_dword v65, v[54:55], off nt
	global_load_dword v66, v[56:57], off nt
	v_or_b32_e32 v42, 16, v58
	v_or_b32_e32 v44, 18, v58
	v_or_b32_e32 v46, 20, v58
	v_or_b32_e32 v48, 22, v58
	v_or_b32_e32 v50, 24, v58
	v_or_b32_e32 v52, 26, v58
	v_or_b32_e32 v54, 28, v58
	v_or_b32_e32 v56, 30, v58
	v_mad_i64_i32 v[42:43], s[14:15], v42, s16, v[40:41]
	v_mad_i64_i32 v[44:45], s[14:15], v44, s16, v[40:41]
	v_mad_i64_i32 v[46:47], s[14:15], v46, s16, v[40:41]
	v_mad_i64_i32 v[48:49], s[14:15], v48, s16, v[40:41]
	v_mad_i64_i32 v[50:51], s[14:15], v50, s16, v[40:41]
	v_mad_i64_i32 v[52:53], s[14:15], v52, s16, v[40:41]
	v_mad_i64_i32 v[54:55], s[14:15], v54, s16, v[40:41]
	v_mad_i64_i32 v[56:57], s[14:15], v56, s16, v[40:41]
	global_load_dword v67, v[42:43], off nt
	global_load_dword v68, v[44:45], off nt
	global_load_dword v69, v[46:47], off nt
	global_load_dword v70, v[48:49], off nt
	global_load_dword v71, v[50:51], off nt
	global_load_dword v72, v[52:53], off nt
	global_load_dword v73, v[54:55], off nt
	global_load_dword v74, v[56:57], off nt
	v_or_b32_e32 v42, 32, v58
	v_or_b32_e32 v44, 34, v58
	v_or_b32_e32 v46, 36, v58
	v_or_b32_e32 v48, 38, v58
	v_or_b32_e32 v50, 40, v58
	v_or_b32_e32 v52, 42, v58
	v_or_b32_e32 v54, 44, v58
	v_or_b32_e32 v56, 46, v58
	v_mad_i64_i32 v[42:43], s[14:15], v42, s16, v[40:41]
	v_mad_i64_i32 v[44:45], s[14:15], v44, s16, v[40:41]
	v_mad_i64_i32 v[46:47], s[14:15], v46, s16, v[40:41]
	v_mad_i64_i32 v[48:49], s[14:15], v48, s16, v[40:41]
	v_mad_i64_i32 v[50:51], s[14:15], v50, s16, v[40:41]
	v_mad_i64_i32 v[52:53], s[14:15], v52, s16, v[40:41]
	v_mad_i64_i32 v[54:55], s[14:15], v54, s16, v[40:41]
	v_mad_i64_i32 v[56:57], s[14:15], v56, s16, v[40:41]
	global_load_dword v75, v[42:43], off nt
	global_load_dword v76, v[44:45], off nt
	global_load_dword v77, v[46:47], off nt
	global_load_dword v78, v[48:49], off nt
	global_load_dword v79, v[50:51], off nt
	global_load_dword v80, v[52:53], off nt
	global_load_dword v81, v[54:55], off nt
	s_nop 0
	global_load_dword v56, v[56:57], off nt
	v_or_b32_e32 v42, 48, v58
	v_or_b32_e32 v44, 50, v58
	v_or_b32_e32 v46, 52, v58
	v_or_b32_e32 v48, 54, v58
	v_or_b32_e32 v50, 56, v58
	v_or_b32_e32 v52, 58, v58
	v_or_b32_e32 v54, 60, v58
	v_or_b32_e32 v57, 62, v58
	v_mad_i64_i32 v[42:43], s[14:15], v42, s16, v[40:41]
	v_mad_i64_i32 v[44:45], s[14:15], v44, s16, v[40:41]
	v_mad_i64_i32 v[46:47], s[14:15], v46, s16, v[40:41]
	v_mad_i64_i32 v[48:49], s[14:15], v48, s16, v[40:41]
	v_mad_i64_i32 v[50:51], s[14:15], v50, s16, v[40:41]
	v_mad_i64_i32 v[52:53], s[14:15], v52, s16, v[40:41]
	v_mad_i64_i32 v[54:55], s[14:15], v54, s16, v[40:41]
	v_mad_i64_i32 v[40:41], s[14:15], v57, s16, v[40:41]
	global_load_dword v42, v[42:43], off nt
	s_nop 0
	global_load_dword v43, v[44:45], off nt
	s_nop 0
	global_load_dword v44, v[46:47], off nt
	global_load_dword v45, v[48:49], off nt
	s_nop 0
	global_load_dword v46, v[50:51], off nt
	global_load_dword v47, v[52:53], off nt
	global_load_dword v48, v[54:55], off nt
	s_nop 0
	global_load_dword v40, v[40:41], off nt
	s_waitcnt vmcnt(0)
; __device__ __forceinline__ unsigned pk2(float lo, float hi) { f32v2 v = {lo, hi}; bf16v2 r = __builtin_convertvector(v, bf16v2); return __builtin_bit_cast(unsigned, r); }
; #define LAS __attribute__((address_space(3)))
; #define LDS_WAIT() asm volatile("s_waitcnt lgkmcnt(0)" ::: "memory")
; __device__ __forceinline__ void transpose_item(const float* W, int K, int N, bf16* WT, int k0, int n0, int dst_row0, LAS float* scr, int lane) {
;     ...
; #pragma unroll
;     for (int i = 0; i < 32; ++i) scr[(2 * i + (lane >> 5)) * 33 + (lane & 31)] = wv[i];
;     LDS_WAIT(); asm volatile("" ::: "memory");
;     const int c = lane & 7;
; #pragma unroll
;     for (int j = 0; j < 4; ++j) { const int n = (lane >> 3) + 8 * j; const LAS float* s = scr + (8 * c) * 33 + n;
;         v4u o; o.x = pk2(s[0 * 33], s[1 * 33]); o.y = pk2(s[2 * 33], s[3 * 33]); o.z = pk2(s[4 * 33], s[5 * 33]); o.w = pk2(s[6 * 33], s[7 * 33]);
;         *(v4u*)(WT + (size_t)(dst_row0 + n) * K + k0 + 8 * c) = o; }
;     LDS_WAIT(); asm volatile("" ::: "memory");
	ds_write2_b32 v27, v59, v60 offset1:66
	s_waitcnt vmcnt(28)
	ds_write2_b32 v27, v61, v62 offset0:132 offset1:198
	s_waitcnt vmcnt(26)
	ds_write2_b32 v33, v63, v64 offset0:8 offset1:74
	s_waitcnt vmcnt(24)
	ds_write2_b32 v33, v65, v66 offset0:140 offset1:206
	s_waitcnt vmcnt(22)
	ds_write2_b32 v34, v67, v68 offset0:16 offset1:82
	s_waitcnt vmcnt(20)
	ds_write2_b32 v34, v69, v70 offset0:148 offset1:214
	s_waitcnt vmcnt(18)
	ds_write2_b32 v35, v71, v72 offset0:24 offset1:90
	s_waitcnt vmcnt(16)
	ds_write2_b32 v35, v73, v74 offset0:156 offset1:222
	s_waitcnt vmcnt(14)
	ds_write2_b32 v36, v75, v76 offset0:32 offset1:98
	s_waitcnt vmcnt(12)
	ds_write2_b32 v36, v77, v78 offset0:164 offset1:230
	s_waitcnt vmcnt(10)
	ds_write2_b32 v37, v79, v80 offset0:40 offset1:106
	s_waitcnt vmcnt(8)
	ds_write2_b32 v37, v81, v56 offset0:172 offset1:238
	s_waitcnt vmcnt(6)
	ds_write2_b32 v38, v42, v43 offset0:48 offset1:114
	s_waitcnt vmcnt(4)
	ds_write2_b32 v38, v44, v45 offset0:180 offset1:246
	s_waitcnt vmcnt(2)
	ds_write2_b32 v39, v46, v47 offset0:56 offset1:122
	s_waitcnt vmcnt(0)
	ds_write2_b32 v39, v48, v40 offset0:188 offset1:254
	s_waitcnt lgkmcnt(0)
	s_ashr_i32 s21, s20, 31
	ds_read2_b32 v[44:45], v29 offset0:33 offset1:41
	ds_read2_b32 v[46:47], v29 offset1:8
	ds_read2_b32 v[48:49], v29 offset0:66 offset1:74
	ds_read2_b32 v[50:51], v29 offset0:99 offset1:107
	ds_read2_b32 v[52:53], v29 offset0:132 offset1:140
	ds_read2_b32 v[54:55], v29 offset0:165 offset1:173
	ds_read2_b32 v[56:57], v29 offset0:198 offset1:206
	ds_read2_b32 v[58:59], v29 offset0:231 offset1:239
	s_lshl_b64 s[14:15], s[20:21], 1
	s_add_u32 s4, s4, s14
	v_add_u32_e32 v62, s26, v28
	s_addc_u32 s5, s5, s15
	v_ashrrev_i32_e32 v63, 31, v62
	v_lshl_add_u64 v[60:61], s[4:5], 0, v[178:179]
	v_lshlrev_b64 v[62:63], 11, v[62:63]
	s_waitcnt lgkmcnt(6)
	v_cvt_pk_bf16_f32 v40, v46, v44
	s_waitcnt lgkmcnt(4)
	v_cvt_pk_bf16_f32 v41, v48, v50
	s_waitcnt lgkmcnt(2)
	v_cvt_pk_bf16_f32 v42, v52, v54
	s_waitcnt lgkmcnt(0)
	v_cvt_pk_bf16_f32 v43, v56, v58
	v_lshl_add_u64 v[62:63], v[60:61], 0, v[62:63]
	v_add_u32_e32 v44, s26, v30
	global_store_dwordx4 v[62:63], v[40:43], off sc0 sc1
	s_nop 1
	v_cvt_pk_bf16_f32 v40, v47, v45
	v_ashrrev_i32_e32 v45, 31, v44
	v_cvt_pk_bf16_f32 v41, v49, v51
	v_cvt_pk_bf16_f32 v42, v53, v55
	v_cvt_pk_bf16_f32 v43, v57, v59
	v_lshlrev_b64 v[44:45], 11, v[44:45]
	ds_read2_b32 v[46:47], v29 offset0:49 offset1:57
	ds_read2_b32 v[48:49], v29 offset0:16 offset1:24
	ds_read2_b32 v[50:51], v29 offset0:82 offset1:90
	ds_read2_b32 v[52:53], v29 offset0:115 offset1:123
	ds_read2_b32 v[54:55], v29 offset0:148 offset1:156
	ds_read2_b32 v[56:57], v29 offset0:181 offset1:189
	ds_read2_b32 v[58:59], v29 offset0:214 offset1:222
	ds_read2_b32 v[62:63], v29 offset0:247 offset1:255
	v_lshl_add_u64 v[44:45], v[60:61], 0, v[44:45]
	global_store_dwordx4 v[44:45], v[40:43], off sc0 sc1
	v_add_u32_e32 v44, s26, v31
	v_ashrrev_i32_e32 v45, 31, v44
	v_lshlrev_b64 v[44:45], 11, v[44:45]
	s_waitcnt lgkmcnt(6)
	v_cvt_pk_bf16_f32 v40, v48, v46
	s_waitcnt lgkmcnt(4)
	v_cvt_pk_bf16_f32 v41, v50, v52
	s_waitcnt lgkmcnt(2)
	v_cvt_pk_bf16_f32 v42, v54, v56
	s_waitcnt lgkmcnt(0)
	v_cvt_pk_bf16_f32 v43, v58, v62
	v_lshl_add_u64 v[44:45], v[60:61], 0, v[44:45]
	global_store_dwordx4 v[44:45], v[40:43], off sc0 sc1
	v_add_u32_e32 v44, s26, v32
	v_ashrrev_i32_e32 v45, 31, v44
	v_lshlrev_b64 v[44:45], 11, v[44:45]
	v_cvt_pk_bf16_f32 v40, v49, v47
	v_cvt_pk_bf16_f32 v41, v51, v53
	v_cvt_pk_bf16_f32 v42, v55, v57
	v_cvt_pk_bf16_f32 v43, v59, v63
	v_lshl_add_u64 v[44:45], v[60:61], 0, v[44:45]
	global_store_dwordx4 v[44:45], v[40:43], off sc0 sc1
	s_waitcnt lgkmcnt(0)

; __device__ __forceinline__ void transpose_item(const float* W, int K, int N, bf16* WT, int k0, int n0, int dst_row0, LAS float* scr, int lane) {
;     float wv[32];
; #pragma unroll
;     for (int i = 0; i < 32; ++i) wv[i] = __builtin_nontemporal_load(W + (size_t)(k0 + 2 * i + (lane >> 5)) * N + n0 + (lane & 31));
; __device__ __forceinline__ void convert_weights(const Args& A, int l, LAS unsigned char* lds, int gw, int ngw, int wave, int lane) {
;     ...
;         r -= I_IN;
;         if (r < I_BS) { transpose_item(w_bs, 512, DM, WB + WO_WBS, (r / 32) * 64, (r % 32) * 32, (r % 32) * 32, scr, lane); continue; } r -= I_BS;
;         if (r < I_BP) { transpose_item(w_bp, 256, DM, WB + WO_WBP, (r / 32) * 64, (r % 32) * 32, (r % 32) * 32, scr, lane); continue; } r -= I_BP;
;         if (r < I_BP) { transpose_item(w_bg, 256, DM, WB + WO_WBG, (r / 32) * 64, (r % 32) * 32, (r % 32) * 32, scr, lane); continue; } r -= I_BP;
;         if (r < I_O)  { transpose_item(w_o, DM, DM, WB + WO_WO, (r / 32) * 64, (r % 32) * 32, (r % 32) * 32, scr, lane); continue; } r -= I_O;
;         if (r < I_F1) { transpose_item(w_f1, DM, D_FF, WB + WO_WF1, (r / 128) * 64, (r % 128) * 32, (r % 128) * 32, scr, lane); continue; } r -= I_F1;
;         transpose_item(w_f2, D_FF, DM, WB + WO_WF2, (r / 32) * 64, (r % 32) * 32, (r % 32) * 32, scr, lane);
.LBB0_56:
	s_cmpk_gt_i32 s25, 0xa7f
	s_mov_b64 s[4:5], -1
	s_cbranch_scc0 .LBB0_78
	s_cmpk_gt_u32 s25, 0xb7f
	s_cbranch_scc0 .LBB0_75
	s_cmpk_gt_u32 s25, 0xbff
	s_cbranch_scc0 .LBB0_72
	s_cmpk_gt_u32 s25, 0xc7f
	s_cbranch_scc0 .LBB0_69
	s_cmpk_gt_u32 s25, 0xe7f
	s_cbranch_scc0 .LBB0_66
	s_cmpk_gt_u32 s25, 0x167f
	s_cbranch_scc0 .LBB0_63
	s_and_b32 s5, s23, 0x7fffffc0
	s_and_b32 s4, s17, 0x3e0
	v_or_b32_e32 v40, s5, v26
	s_lshl_b32 s94, s4, 2
	v_mov_b32_e32 v41, v179
	v_or_b32_e32 v46, 2, v40
	v_mov_b32_e32 v47, v179
	v_or_b32_e32 v48, 4, v40
	v_mov_b32_e32 v49, v179
	v_or_b32_e32 v50, 6, v40
	v_mov_b32_e32 v51, v179
	v_or_b32_e32 v52, 8, v40
	v_mov_b32_e32 v53, v179
	v_or_b32_e32 v54, 10, v40
	v_mov_b32_e32 v55, v179
	v_or_b32_e32 v56, 12, v40
	v_mov_b32_e32 v57, v179
	v_or_b32_e32 v58, 14, v40
	v_mov_b32_e32 v59, v179
	v_lshl_add_u64 v[42:43], v[0:1], 0, s[94:95]
	v_lshlrev_b64 v[44:45], 12, v[40:41]
	v_lshlrev_b64 v[46:47], 12, v[46:47]
	v_lshlrev_b64 v[48:49], 12, v[48:49]
	v_lshlrev_b64 v[50:51], 12, v[50:51]
	v_lshlrev_b64 v[52:53], 12, v[52:53]
	v_lshlrev_b64 v[54:55], 12, v[54:55]
	v_lshlrev_b64 v[56:57], 12, v[56:57]
	v_lshlrev_b64 v[58:59], 12, v[58:59]
	v_lshl_add_u64 v[44:45], v[42:43], 0, v[44:45]
	v_lshl_add_u64 v[46:47], v[42:43], 0, v[46:47]
	v_lshl_add_u64 v[48:49], v[42:43], 0, v[48:49]
	v_lshl_add_u64 v[50:51], v[42:43], 0, v[50:51]
	v_lshl_add_u64 v[52:53], v[42:43], 0, v[52:53]
	v_lshl_add_u64 v[54:55], v[42:43], 0, v[54:55]
	v_lshl_add_u64 v[56:57], v[42:43], 0, v[56:57]
	v_lshl_add_u64 v[58:59], v[42:43], 0, v[58:59]
	global_load_dword v60, v[44:45], off nt
	global_load_dword v61, v[46:47], off nt
	global_load_dword v62, v[48:49], off nt
	global_load_dword v63, v[50:51], off nt
	global_load_dword v64, v[52:53], off nt
	global_load_dword v65, v[54:55], off nt
	global_load_dword v66, v[56:57], off nt
	global_load_dword v67, v[58:59], off nt
	v_or_b32_e32 v44, 16, v40
	v_mov_b32_e32 v45, v179
	v_or_b32_e32 v46, 18, v40
	v_mov_b32_e32 v47, v179
	v_or_b32_e32 v48, 20, v40
	v_mov_b32_e32 v49, v179
	v_or_b32_e32 v50, 22, v40
	v_mov_b32_e32 v51, v179
	v_or_b32_e32 v52, 24, v40
	v_mov_b32_e32 v53, v179
	v_or_b32_e32 v54, 26, v40
	v_mov_b32_e32 v55, v179
	v_or_b32_e32 v56, 28, v40
	v_mov_b32_e32 v57, v179
	v_or_b32_e32 v58, 30, v40
	v_mov_b32_e32 v59, v179
	v_lshlrev_b64 v[44:45], 12, v[44:45]
	v_lshlrev_b64 v[46:47], 12, v[46:47]
	v_lshlrev_b64 v[48:49], 12, v[48:49]
	v_lshlrev_b64 v[50:51], 12, v[50:51]
	v_lshlrev_b64 v[52:53], 12, v[52:53]
	v_lshlrev_b64 v[54:55], 12, v[54:55]
	v_lshlrev_b64 v[56:57], 12, v[56:57]
	v_lshlrev_b64 v[58:59], 12, v[58:59]
	v_lshl_add_u64 v[44:45], v[42:43], 0, v[44:45]
	v_lshl_add_u64 v[46:47], v[42:43], 0, v[46:47]
	v_lshl_add_u64 v[48:49], v[42:43], 0, v[48:49]
	v_lshl_add_u64 v[50:51], v[42:43], 0, v[50:51]
	v_lshl_add_u64 v[52:53], v[42:43], 0, v[52:53]
	v_lshl_add_u64 v[54:55], v[42:43], 0, v[54:55]
	v_lshl_add_u64 v[56:57], v[42:43], 0, v[56:57]
	v_lshl_add_u64 v[58:59], v[42:43], 0, v[58:59]
	global_load_dword v68, v[44:45], off nt
	global_load_dword v69, v[46:47], off nt
	global_load_dword v70, v[48:49], off nt
	global_load_dword v71, v[50:51], off nt
	global_load_dword v72, v[52:53], off nt
	global_load_dword v73, v[54:55], off nt
	global_load_dword v74, v[56:57], off nt
	global_load_dword v75, v[58:59], off nt
	v_or_b32_e32 v44, 32, v40
	v_mov_b32_e32 v45, v179
	v_or_b32_e32 v46, 34, v40
	v_mov_b32_e32 v47, v179
	v_or_b32_e32 v48, 36, v40
	v_mov_b32_e32 v49, v179
	v_or_b32_e32 v50, 38, v40
	v_mov_b32_e32 v51, v179
	v_or_b32_e32 v52, 40, v40
	v_mov_b32_e32 v53, v179
	v_or_b32_e32 v54, 42, v40
	v_mov_b32_e32 v55, v179
	v_or_b32_e32 v56, 44, v40
	v_mov_b32_e32 v57, v179
	v_or_b32_e32 v58, 46, v40
	v_mov_b32_e32 v59, v179
	v_lshlrev_b64 v[44:45], 12, v[44:45]
	v_lshlrev_b64 v[46:47], 12, v[46:47]
	v_lshlrev_b64 v[48:49], 12, v[48:49]
	v_lshlrev_b64 v[50:51], 12, v[50:51]
	v_lshlrev_b64 v[52:53], 12, v[52:53]
	v_lshlrev_b64 v[54:55], 12, v[54:55]
	v_lshlrev_b64 v[56:57], 12, v[56:57]
	v_lshlrev_b64 v[58:59], 12, v[58:59]
	v_lshl_add_u64 v[44:45], v[42:43], 0, v[44:45]
	v_lshl_add_u64 v[46:47], v[42:43], 0, v[46:47]
	v_lshl_add_u64 v[48:49], v[42:43], 0, v[48:49]
	v_lshl_add_u64 v[50:51], v[42:43], 0, v[50:51]
	v_lshl_add_u64 v[52:53], v[42:43], 0, v[52:53]
	v_lshl_add_u64 v[54:55], v[42:43], 0, v[54:55]
	v_lshl_add_u64 v[56:57], v[42:43], 0, v[56:57]
	v_lshl_add_u64 v[58:59], v[42:43], 0, v[58:59]
	global_load_dword v76, v[44:45], off nt
	global_load_dword v77, v[46:47], off nt
	global_load_dword v78, v[48:49], off nt
	global_load_dword v79, v[50:51], off nt
	global_load_dword v80, v[52:53], off nt
	global_load_dword v81, v[54:55], off nt
	global_load_dword v82, v[56:57], off nt
	s_nop 0
	global_load_dword v58, v[58:59], off nt
	v_or_b32_e32 v44, 48, v40
	v_mov_b32_e32 v45, v179
	v_or_b32_e32 v46, 50, v40
	v_mov_b32_e32 v47, v179
	v_or_b32_e32 v48, 52, v40
	v_mov_b32_e32 v49, v179
	v_or_b32_e32 v50, 54, v40
	v_or_b32_e32 v52, 56, v40
	v_or_b32_e32 v54, 58, v40
	v_or_b32_e32 v56, 60, v40
	v_or_b32_e32 v40, 62, v40
	v_lshlrev_b64 v[44:45], 12, v[44:45]
	v_lshlrev_b64 v[46:47], 12, v[46:47]
	v_lshlrev_b64 v[48:49], 12, v[48:49]
	v_mov_b32_e32 v51, v179
	v_mov_b32_e32 v53, v179
	v_mov_b32_e32 v55, v179
	v_mov_b32_e32 v57, v179
	v_lshlrev_b64 v[40:41], 12, v[40:41]
	v_lshl_add_u64 v[44:45], v[42:43], 0, v[44:45]
	v_lshl_add_u64 v[46:47], v[42:43], 0, v[46:47]
	v_lshl_add_u64 v[48:49], v[42:43], 0, v[48:49]
	v_lshlrev_b64 v[50:51], 12, v[50:51]
	v_lshlrev_b64 v[52:53], 12, v[52:53]
	v_lshlrev_b64 v[54:55], 12, v[54:55]
	v_lshlrev_b64 v[56:57], 12, v[56:57]
	v_lshl_add_u64 v[40:41], v[42:43], 0, v[40:41]
	v_lshl_add_u64 v[50:51], v[42:43], 0, v[50:51]
	v_lshl_add_u64 v[52:53], v[42:43], 0, v[52:53]
	v_lshl_add_u64 v[54:55], v[42:43], 0, v[54:55]
	v_lshl_add_u64 v[56:57], v[42:43], 0, v[56:57]
	global_load_dword v42, v[44:45], off nt
	global_load_dword v43, v[46:47], off nt
	s_nop 0
	global_load_dword v44, v[48:49], off nt
	global_load_dword v45, v[50:51], off nt
	global_load_dword v46, v[52:53], off nt
	global_load_dword v47, v[54:55], off nt
	s_nop 0
	global_load_dword v48, v[56:57], off nt
	s_nop 0
	global_load_dword v40, v[40:41], off nt
	s_waitcnt vmcnt(0)
; __device__ __forceinline__ unsigned pk2(float lo, float hi) { f32v2 v = {lo, hi}; bf16v2 r = __builtin_convertvector(v, bf16v2); return __builtin_bit_cast(unsigned, r); }
; #define LAS __attribute__((address_space(3)))
; #define LDS_WAIT() asm volatile("s_waitcnt lgkmcnt(0)" ::: "memory")
; __device__ __forceinline__ void transpose_item(const float* W, int K, int N, bf16* WT, int k0, int n0, int dst_row0, LAS float* scr, int lane) {
;     ...
;     for (int i = 0; i < 32; ++i) scr[(2 * i + (lane >> 5)) * 33 + (lane & 31)] = wv[i];
;     LDS_WAIT(); asm volatile("" ::: "memory");
;     const int c = lane & 7;
; #pragma unroll
;     for (int j = 0; j < 4; ++j) { const int n = (lane >> 3) + 8 * j; const LAS float* s = scr + (8 * c) * 33 + n;
;         v4u o; o.x = pk2(s[0 * 33], s[1 * 33]); o.y = pk2(s[2 * 33], s[3 * 33]); o.z = pk2(s[4 * 33], s[5 * 33]); o.w = pk2(s[6 * 33], s[7 * 33]);
;         *(v4u*)(WT + (size_t)(dst_row0 + n) * K + k0 + 8 * c) = o; }
;     LDS_WAIT(); asm volatile("" ::: "memory");
; __device__ __forceinline__ void convert_weights(const Args& A, int l, LAS unsigned char* lds, int gw, int ngw, int wave, int lane) {
;     ...
;         if (r < I_F1) { transpose_item(w_f1, DM, D_FF, WB + WO_WF1, (r / 128) * 64, (r % 128) * 32, (r % 128) * 32, scr, lane); continue; } r -= I_F1;
	ds_write2_b32 v27, v60, v61 offset1:66
	s_waitcnt vmcnt(28)
	ds_write2_b32 v27, v62, v63 offset0:132 offset1:198
	s_waitcnt vmcnt(26)
	ds_write2_b32 v33, v64, v65 offset0:8 offset1:74
	s_waitcnt vmcnt(24)
	ds_write2_b32 v33, v66, v67 offset0:140 offset1:206
	s_waitcnt vmcnt(22)
	ds_write2_b32 v34, v68, v69 offset0:16 offset1:82
	s_waitcnt vmcnt(20)
	ds_write2_b32 v34, v70, v71 offset0:148 offset1:214
	s_waitcnt vmcnt(18)
	ds_write2_b32 v35, v72, v73 offset0:24 offset1:90
	s_waitcnt vmcnt(16)
	ds_write2_b32 v35, v74, v75 offset0:156 offset1:222
	s_waitcnt vmcnt(14)
	ds_write2_b32 v36, v76, v77 offset0:32 offset1:98
	s_waitcnt vmcnt(12)
	ds_write2_b32 v36, v78, v79 offset0:164 offset1:230
	s_waitcnt vmcnt(10)
	ds_write2_b32 v37, v80, v81 offset0:40 offset1:106
	s_waitcnt vmcnt(8)
	ds_write2_b32 v37, v82, v58 offset0:172 offset1:238
	s_waitcnt vmcnt(6)
	ds_write2_b32 v38, v42, v43 offset0:48 offset1:114
	s_waitcnt vmcnt(4)
	ds_write2_b32 v38, v44, v45 offset0:180 offset1:246
	s_waitcnt vmcnt(2)
	ds_write2_b32 v39, v46, v47 offset0:56 offset1:122
	s_waitcnt vmcnt(0)
	ds_write2_b32 v39, v48, v40 offset0:188 offset1:254
	s_waitcnt lgkmcnt(0)
	ds_read2_b32 v[44:45], v29 offset0:33 offset1:41
	ds_read2_b32 v[46:47], v29 offset1:8
	ds_read2_b32 v[48:49], v29 offset0:66 offset1:74
	ds_read2_b32 v[50:51], v29 offset0:99 offset1:107
	ds_read2_b32 v[52:53], v29 offset0:132 offset1:140
	ds_read2_b32 v[54:55], v29 offset0:165 offset1:173
	ds_read2_b32 v[56:57], v29 offset0:198 offset1:206
	ds_read2_b32 v[58:59], v29 offset0:231 offset1:239
	s_lshl_b32 s94, s5, 1
	s_waitcnt lgkmcnt(6)
	v_cvt_pk_bf16_f32 v40, v46, v44
	v_or_b32_e32 v44, s4, v28
	v_lshl_add_u64 v[60:61], v[2:3], 0, s[94:95]
	v_lshlrev_b32_e32 v62, 13, v44
	v_mov_b32_e32 v63, v179
	s_waitcnt lgkmcnt(4)
	v_cvt_pk_bf16_f32 v41, v48, v50
	s_waitcnt lgkmcnt(2)
	v_cvt_pk_bf16_f32 v42, v52, v54
	s_waitcnt lgkmcnt(0)
	v_cvt_pk_bf16_f32 v43, v56, v58
	v_lshl_add_u64 v[62:63], v[60:61], 0, v[62:63]
	global_store_dwordx4 v[62:63], v[40:43], off sc0 sc1
	v_or_b32_e32 v44, s4, v30
	v_lshlrev_b32_e32 v44, 13, v44
	v_cvt_pk_bf16_f32 v40, v47, v45
	v_cvt_pk_bf16_f32 v41, v49, v51
	v_cvt_pk_bf16_f32 v42, v53, v55
	v_cvt_pk_bf16_f32 v43, v57, v59
	ds_read2_b32 v[46:47], v29 offset0:49 offset1:57
	ds_read2_b32 v[48:49], v29 offset0:16 offset1:24
	ds_read2_b32 v[50:51], v29 offset0:82 offset1:90
	ds_read2_b32 v[52:53], v29 offset0:115 offset1:123
	ds_read2_b32 v[54:55], v29 offset0:148 offset1:156
	ds_read2_b32 v[56:57], v29 offset0:181 offset1:189
	ds_read2_b32 v[58:59], v29 offset0:214 offset1:222
	ds_read2_b32 v[62:63], v29 offset0:247 offset1:255
	v_mov_b32_e32 v45, v179
	v_lshl_add_u64 v[44:45], v[60:61], 0, v[44:45]
	global_store_dwordx4 v[44:45], v[40:43], off sc0 sc1
	v_or_b32_e32 v44, s4, v31
	v_lshlrev_b32_e32 v44, 13, v44
	v_mov_b32_e32 v45, v179
	s_waitcnt lgkmcnt(6)
	v_cvt_pk_bf16_f32 v40, v48, v46
	s_waitcnt lgkmcnt(4)
	v_cvt_pk_bf16_f32 v41, v50, v52
	s_waitcnt lgkmcnt(2)
	v_cvt_pk_bf16_f32 v42, v54, v56
	s_waitcnt lgkmcnt(0)
	v_cvt_pk_bf16_f32 v43, v58, v62
	v_lshl_add_u64 v[44:45], v[60:61], 0, v[44:45]
	global_store_dwordx4 v[44:45], v[40:43], off sc0 sc1
	v_or_b32_e32 v44, s4, v32
	v_lshlrev_b32_e32 v44, 13, v44
	v_mov_b32_e32 v45, v179
	v_cvt_pk_bf16_f32 v40, v49, v47
	v_cvt_pk_bf16_f32 v41, v51, v53
	v_cvt_pk_bf16_f32 v42, v55, v57
	v_cvt_pk_bf16_f32 v43, v59, v63
	v_lshl_add_u64 v[44:45], v[60:61], 0, v[44:45]
	global_store_dwordx4 v[44:45], v[40:43], off sc0 sc1
	s_waitcnt lgkmcnt(0)
	s_mov_b64 s[4:5], 0
.LBB0_63:
	s_andn2_b64 vcc, exec, s[4:5]
	s_cbranch_vccnz .LBB0_65
	s_add_i32 s4, s25, 0xfffff180
	s_lshr_b32 s4, s4, 1
	s_and_b32 s5, s4, 0x7fffffc0
	s_and_b32 s4, s17, 0xfe0
	v_or_b32_e32 v40, s5, v26
	s_lshl_b32 s94, s4, 2
	v_mov_b32_e32 v41, v179
	v_or_b32_e32 v46, 2, v40
	v_mov_b32_e32 v47, v179
	v_or_b32_e32 v48, 4, v40
	v_mov_b32_e32 v49, v179
	v_or_b32_e32 v50, 6, v40
	v_mov_b32_e32 v51, v179
	v_or_b32_e32 v52, 8, v40
	v_mov_b32_e32 v53, v179
	v_or_b32_e32 v54, 10, v40
	v_mov_b32_e32 v55, v179
	v_or_b32_e32 v56, 12, v40
	v_mov_b32_e32 v57, v179
	v_or_b32_e32 v58, 14, v40
	v_mov_b32_e32 v59, v179
	v_lshl_add_u64 v[42:43], v[4:5], 0, s[94:95]
	v_lshlrev_b64 v[44:45], 14, v[40:41]
	v_lshlrev_b64 v[46:47], 14, v[46:47]
	v_lshlrev_b64 v[48:49], 14, v[48:49]
	v_lshlrev_b64 v[50:51], 14, v[50:51]
	v_lshlrev_b64 v[52:53], 14, v[52:53]
	v_lshlrev_b64 v[54:55], 14, v[54:55]
	v_lshlrev_b64 v[56:57], 14, v[56:57]
	v_lshlrev_b64 v[58:59], 14, v[58:59]
	v_lshl_add_u64 v[44:45], v[42:43], 0, v[44:45]
	v_lshl_add_u64 v[46:47], v[42:43], 0, v[46:47]
	v_lshl_add_u64 v[48:49], v[42:43], 0, v[48:49]
	v_lshl_add_u64 v[50:51], v[42:43], 0, v[50:51]
	v_lshl_add_u64 v[52:53], v[42:43], 0, v[52:53]
	v_lshl_add_u64 v[54:55], v[42:43], 0, v[54:55]
	v_lshl_add_u64 v[56:57], v[42:43], 0, v[56:57]
	v_lshl_add_u64 v[58:59], v[42:43], 0, v[58:59]
	global_load_dword v60, v[44:45], off nt
	global_load_dword v61, v[46:47], off nt
	global_load_dword v62, v[48:49], off nt
	global_load_dword v63, v[50:51], off nt
	global_load_dword v64, v[52:53], off nt
	global_load_dword v65, v[54:55], off nt
	global_load_dword v66, v[56:57], off nt
	global_load_dword v67, v[58:59], off nt
	v_or_b32_e32 v44, 16, v40
	v_mov_b32_e32 v45, v179
	v_or_b32_e32 v46, 18, v40
	v_mov_b32_e32 v47, v179
	v_or_b32_e32 v48, 20, v40
	v_mov_b32_e32 v49, v179
	v_or_b32_e32 v50, 22, v40
	v_mov_b32_e32 v51, v179
	v_or_b32_e32 v52, 24, v40
	v_mov_b32_e32 v53, v179
	v_or_b32_e32 v54, 26, v40
	v_mov_b32_e32 v55, v179
	v_or_b32_e32 v56, 28, v40
	v_mov_b32_e32 v57, v179
	v_or_b32_e32 v58, 30, v40
	v_mov_b32_e32 v59, v179
	v_lshlrev_b64 v[44:45], 14, v[44:45]
; __device__ __forceinline__ void transpose_item(const float* W, int K, int N, bf16* WT, int k0, int n0, int dst_row0, LAS float* scr, int lane) {
;     float wv[32];
; #pragma unroll
;     for (int i = 0; i < 32; ++i) wv[i] = __builtin_nontemporal_load(W + (size_t)(k0 + 2 * i + (lane >> 5)) * N + n0 + (lane & 31));
	v_lshlrev_b64 v[46:47], 14, v[46:47]
	v_lshlrev_b64 v[48:49], 14, v[48:49]
	v_lshlrev_b64 v[50:51], 14, v[50:51]
	v_lshlrev_b64 v[52:53], 14, v[52:53]
	v_lshlrev_b64 v[54:55], 14, v[54:55]
	v_lshlrev_b64 v[56:57], 14, v[56:57]
	v_lshlrev_b64 v[58:59], 14, v[58:59]
	v_lshl_add_u64 v[44:45], v[42:43], 0, v[44:45]
	v_lshl_add_u64 v[46:47], v[42:43], 0, v[46:47]
	v_lshl_add_u64 v[48:49], v[42:43], 0, v[48:49]
	v_lshl_add_u64 v[50:51], v[42:43], 0, v[50:51]
	v_lshl_add_u64 v[52:53], v[42:43], 0, v[52:53]
	v_lshl_add_u64 v[54:55], v[42:43], 0, v[54:55]
	v_lshl_add_u64 v[56:57], v[42:43], 0, v[56:57]
	v_lshl_add_u64 v[58:59], v[42:43], 0, v[58:59]
	global_load_dword v68, v[44:45], off nt
	global_load_dword v69, v[46:47], off nt
	global_load_dword v70, v[48:49], off nt
	global_load_dword v71, v[50:51], off nt
	global_load_dword v72, v[52:53], off nt
	global_load_dword v73, v[54:55], off nt
	global_load_dword v74, v[56:57], off nt
	global_load_dword v75, v[58:59], off nt
	v_or_b32_e32 v44, 32, v40
	v_mov_b32_e32 v45, v179
	v_or_b32_e32 v46, 34, v40
	v_mov_b32_e32 v47, v179
	v_or_b32_e32 v48, 36, v40
	v_mov_b32_e32 v49, v179
	v_or_b32_e32 v50, 38, v40
	v_mov_b32_e32 v51, v179
	v_or_b32_e32 v52, 40, v40
	v_mov_b32_e32 v53, v179
	v_or_b32_e32 v54, 42, v40
	v_mov_b32_e32 v55, v179
	v_or_b32_e32 v56, 44, v40
	v_mov_b32_e32 v57, v179
	v_or_b32_e32 v58, 46, v40
	v_mov_b32_e32 v59, v179
	v_lshlrev_b64 v[44:45], 14, v[44:45]
	v_lshlrev_b64 v[46:47], 14, v[46:47]
	v_lshlrev_b64 v[48:49], 14, v[48:49]
	v_lshlrev_b64 v[50:51], 14, v[50:51]
	v_lshlrev_b64 v[52:53], 14, v[52:53]
	v_lshlrev_b64 v[54:55], 14, v[54:55]
	v_lshlrev_b64 v[56:57], 14, v[56:57]
	v_lshlrev_b64 v[58:59], 14, v[58:59]
	v_lshl_add_u64 v[44:45], v[42:43], 0, v[44:45]
	v_lshl_add_u64 v[46:47], v[42:43], 0, v[46:47]
	v_lshl_add_u64 v[48:49], v[42:43], 0, v[48:49]
	v_lshl_add_u64 v[50:51], v[42:43], 0, v[50:51]
	v_lshl_add_u64 v[52:53], v[42:43], 0, v[52:53]
	v_lshl_add_u64 v[54:55], v[42:43], 0, v[54:55]
	v_lshl_add_u64 v[56:57], v[42:43], 0, v[56:57]
	v_lshl_add_u64 v[58:59], v[42:43], 0, v[58:59]
	global_load_dword v76, v[44:45], off nt
	global_load_dword v77, v[46:47], off nt
	global_load_dword v78, v[48:49], off nt
	global_load_dword v79, v[50:51], off nt
	global_load_dword v80, v[52:53], off nt
	global_load_dword v81, v[54:55], off nt
	global_load_dword v82, v[56:57], off nt
	s_nop 0
	global_load_dword v58, v[58:59], off nt
	v_or_b32_e32 v44, 48, v40
	v_mov_b32_e32 v45, v179
	v_or_b32_e32 v46, 50, v40
	v_mov_b32_e32 v47, v179
	v_or_b32_e32 v48, 52, v40
	v_mov_b32_e32 v49, v179
	v_or_b32_e32 v50, 54, v40
	v_or_b32_e32 v52, 56, v40
	v_or_b32_e32 v54, 58, v40
	v_or_b32_e32 v56, 60, v40
	v_or_b32_e32 v40, 62, v40
	v_lshlrev_b64 v[44:45], 14, v[44:45]
	v_lshlrev_b64 v[46:47], 14, v[46:47]
	v_lshlrev_b64 v[48:49], 14, v[48:49]
	v_mov_b32_e32 v51, v179
	v_mov_b32_e32 v53, v179
	v_mov_b32_e32 v55, v179
	v_mov_b32_e32 v57, v179
	v_lshlrev_b64 v[40:41], 14, v[40:41]
	v_lshl_add_u64 v[44:45], v[42:43], 0, v[44:45]
	v_lshl_add_u64 v[46:47], v[42:43], 0, v[46:47]
	v_lshl_add_u64 v[48:49], v[42:43], 0, v[48:49]
	v_lshlrev_b64 v[50:51], 14, v[50:51]
	v_lshlrev_b64 v[52:53], 14, v[52:53]
	v_lshlrev_b64 v[54:55], 14, v[54:55]
	v_lshlrev_b64 v[56:57], 14, v[56:57]
	v_lshl_add_u64 v[40:41], v[42:43], 0, v[40:41]
	v_lshl_add_u64 v[50:51], v[42:43], 0, v[50:51]
	v_lshl_add_u64 v[52:53], v[42:43], 0, v[52:53]
	v_lshl_add_u64 v[54:55], v[42:43], 0, v[54:55]
	v_lshl_add_u64 v[56:57], v[42:43], 0, v[56:57]
	global_load_dword v42, v[44:45], off nt
	global_load_dword v43, v[46:47], off nt
	s_nop 0
	global_load_dword v44, v[48:49], off nt
	global_load_dword v45, v[50:51], off nt
	global_load_dword v46, v[52:53], off nt
	global_load_dword v47, v[54:55], off nt
	s_nop 0
	global_load_dword v48, v[56:57], off nt
	s_nop 0
	global_load_dword v40, v[40:41], off nt
	s_waitcnt vmcnt(0)
; __device__ __forceinline__ unsigned pk2(float lo, float hi) { f32v2 v = {lo, hi}; bf16v2 r = __builtin_convertvector(v, bf16v2); return __builtin_bit_cast(unsigned, r); }
; #define LAS __attribute__((address_space(3)))
; #define LDS_WAIT() asm volatile("s_waitcnt lgkmcnt(0)" ::: "memory")
; __device__ __forceinline__ void transpose_item(const float* W, int K, int N, bf16* WT, int k0, int n0, int dst_row0, LAS float* scr, int lane) {
;     ...
; #pragma unroll
;     for (int i = 0; i < 32; ++i) scr[(2 * i + (lane >> 5)) * 33 + (lane & 31)] = wv[i];
;     LDS_WAIT(); asm volatile("" ::: "memory");
;     const int c = lane & 7;
; #pragma unroll
;     for (int j = 0; j < 4; ++j) { const int n = (lane >> 3) + 8 * j; const LAS float* s = scr + (8 * c) * 33 + n;
;         v4u o; o.x = pk2(s[0 * 33], s[1 * 33]); o.y = pk2(s[2 * 33], s[3 * 33]); o.z = pk2(s[4 * 33], s[5 * 33]); o.w = pk2(s[6 * 33], s[7 * 33]);
;         *(v4u*)(WT + (size_t)(dst_row0 + n) * K + k0 + 8 * c) = o; }
;     LDS_WAIT(); asm volatile("" ::: "memory");
	ds_write2_b32 v27, v60, v61 offset1:66
	s_waitcnt vmcnt(28)
	ds_write2_b32 v27, v62, v63 offset0:132 offset1:198
	s_waitcnt vmcnt(26)
	ds_write2_b32 v33, v64, v65 offset0:8 offset1:74
	s_waitcnt vmcnt(24)
	ds_write2_b32 v33, v66, v67 offset0:140 offset1:206
	s_waitcnt vmcnt(22)
	ds_write2_b32 v34, v68, v69 offset0:16 offset1:82
	s_waitcnt vmcnt(20)
	ds_write2_b32 v34, v70, v71 offset0:148 offset1:214
	s_waitcnt vmcnt(18)
	ds_write2_b32 v35, v72, v73 offset0:24 offset1:90
	s_waitcnt vmcnt(16)
	ds_write2_b32 v35, v74, v75 offset0:156 offset1:222
	s_waitcnt vmcnt(14)
	ds_write2_b32 v36, v76, v77 offset0:32 offset1:98
	s_waitcnt vmcnt(12)
	ds_write2_b32 v36, v78, v79 offset0:164 offset1:230
	s_waitcnt vmcnt(10)
	ds_write2_b32 v37, v80, v81 offset0:40 offset1:106
	s_waitcnt vmcnt(8)
	ds_write2_b32 v37, v82, v58 offset0:172 offset1:238
	s_waitcnt vmcnt(6)
	ds_write2_b32 v38, v42, v43 offset0:48 offset1:114
	s_waitcnt vmcnt(4)
	ds_write2_b32 v38, v44, v45 offset0:180 offset1:246
	s_waitcnt vmcnt(2)
	ds_write2_b32 v39, v46, v47 offset0:56 offset1:122
	s_waitcnt vmcnt(0)
	ds_write2_b32 v39, v48, v40 offset0:188 offset1:254
	s_waitcnt lgkmcnt(0)
	ds_read2_b32 v[44:45], v29 offset0:33 offset1:41
	ds_read2_b32 v[46:47], v29 offset1:8
	ds_read2_b32 v[48:49], v29 offset0:66 offset1:74
	ds_read2_b32 v[50:51], v29 offset0:99 offset1:107
	ds_read2_b32 v[52:53], v29 offset0:132 offset1:140
	ds_read2_b32 v[54:55], v29 offset0:165 offset1:173
	ds_read2_b32 v[56:57], v29 offset0:198 offset1:206
	ds_read2_b32 v[58:59], v29 offset0:231 offset1:239
	s_lshl_b32 s94, s5, 1
	s_waitcnt lgkmcnt(6)
	v_cvt_pk_bf16_f32 v40, v46, v44
	v_or_b32_e32 v44, s4, v28
	v_lshl_add_u64 v[60:61], v[6:7], 0, s[94:95]
	v_lshlrev_b32_e32 v62, 11, v44
	v_mov_b32_e32 v63, v179
	s_waitcnt lgkmcnt(4)
	v_cvt_pk_bf16_f32 v41, v48, v50
	s_waitcnt lgkmcnt(2)
	v_cvt_pk_bf16_f32 v42, v52, v54
	s_waitcnt lgkmcnt(0)
	v_cvt_pk_bf16_f32 v43, v56, v58
	v_lshl_add_u64 v[62:63], v[60:61], 0, v[62:63]
	global_store_dwordx4 v[62:63], v[40:43], off sc0 sc1
	v_or_b32_e32 v44, s4, v30
	v_lshlrev_b32_e32 v44, 11, v44
	v_cvt_pk_bf16_f32 v40, v47, v45
	v_cvt_pk_bf16_f32 v41, v49, v51
	v_cvt_pk_bf16_f32 v42, v53, v55
	v_cvt_pk_bf16_f32 v43, v57, v59
	ds_read2_b32 v[46:47], v29 offset0:49 offset1:57
	ds_read2_b32 v[48:49], v29 offset0:16 offset1:24
	ds_read2_b32 v[50:51], v29 offset0:82 offset1:90
	ds_read2_b32 v[52:53], v29 offset0:115 offset1:123
	ds_read2_b32 v[54:55], v29 offset0:148 offset1:156
	ds_read2_b32 v[56:57], v29 offset0:181 offset1:189
	ds_read2_b32 v[58:59], v29 offset0:214 offset1:222
	ds_read2_b32 v[62:63], v29 offset0:247 offset1:255
	v_mov_b32_e32 v45, v179
	v_lshl_add_u64 v[44:45], v[60:61], 0, v[44:45]
	global_store_dwordx4 v[44:45], v[40:43], off sc0 sc1
	v_or_b32_e32 v44, s4, v31
	v_lshlrev_b32_e32 v44, 11, v44
	v_mov_b32_e32 v45, v179
	s_waitcnt lgkmcnt(6)
	v_cvt_pk_bf16_f32 v40, v48, v46
	s_waitcnt lgkmcnt(4)
	v_cvt_pk_bf16_f32 v41, v50, v52
	s_waitcnt lgkmcnt(2)
	v_cvt_pk_bf16_f32 v42, v54, v56
	s_waitcnt lgkmcnt(0)
	v_cvt_pk_bf16_f32 v43, v58, v62
	v_lshl_add_u64 v[44:45], v[60:61], 0, v[44:45]
	global_store_dwordx4 v[44:45], v[40:43], off sc0 sc1
	v_or_b32_e32 v44, s4, v32
	v_lshlrev_b32_e32 v44, 11, v44
	v_mov_b32_e32 v45, v179
	v_cvt_pk_bf16_f32 v40, v49, v47
	v_cvt_pk_bf16_f32 v41, v51, v53
	v_cvt_pk_bf16_f32 v42, v55, v57
	v_cvt_pk_bf16_f32 v43, v59, v63
	v_lshl_add_u64 v[44:45], v[60:61], 0, v[44:45]
	global_store_dwordx4 v[44:45], v[40:43], off sc0 sc1
	s_waitcnt lgkmcnt(0)

; #define LAS __attribute__((address_space(3)))
; __device__ __forceinline__ void transpose_item(const float* W, int K, int N, bf16* WT, int k0, int n0, int dst_row0, LAS float* scr, int lane) {
;     float wv[32];
; #pragma unroll
;     for (int i = 0; i < 32; ++i) wv[i] = __builtin_nontemporal_load(W + (size_t)(k0 + 2 * i + (lane >> 5)) * N + n0 + (lane & 31));
; __device__ __forceinline__ void convert_weights(const Args& A, int l, LAS unsigned char* lds, int gw, int ngw, int wave, int lane) {
;     ...
;         if (r < I_O)  { transpose_item(w_o, DM, DM, WB + WO_WO, (r / 32) * 64, (r % 32) * 32, (r % 32) * 32, scr, lane); continue; } r -= I_O;
.LBB0_66:
	s_andn2_b64 vcc, exec, s[4:5]
	s_cbranch_vccnz .LBB0_68
	s_add_i32 s4, s23, 0x1400
	s_and_b32 s5, s4, 0x7fffffc0
	s_and_b32 s4, s17, 0x3e0
	v_or_b32_e32 v40, s5, v26
	s_lshl_b32 s94, s4, 2
	v_mov_b32_e32 v41, v179
	v_or_b32_e32 v46, 2, v40
	v_mov_b32_e32 v47, v179
	v_or_b32_e32 v48, 4, v40
	v_mov_b32_e32 v49, v179
	v_or_b32_e32 v50, 6, v40
	v_mov_b32_e32 v51, v179
	v_or_b32_e32 v52, 8, v40
	v_mov_b32_e32 v53, v179
	v_or_b32_e32 v54, 10, v40
	v_mov_b32_e32 v55, v179
	v_or_b32_e32 v56, 12, v40
	v_mov_b32_e32 v57, v179
	v_or_b32_e32 v58, 14, v40
	v_mov_b32_e32 v59, v179
	v_lshl_add_u64 v[42:43], v[8:9], 0, s[94:95]
	v_lshlrev_b64 v[44:45], 12, v[40:41]
	v_lshlrev_b64 v[46:47], 12, v[46:47]
	v_lshlrev_b64 v[48:49], 12, v[48:49]
	v_lshlrev_b64 v[50:51], 12, v[50:51]
	v_lshlrev_b64 v[52:53], 12, v[52:53]
	v_lshlrev_b64 v[54:55], 12, v[54:55]
	v_lshlrev_b64 v[56:57], 12, v[56:57]
	v_lshlrev_b64 v[58:59], 12, v[58:59]
	v_lshl_add_u64 v[44:45], v[42:43], 0, v[44:45]
	v_lshl_add_u64 v[46:47], v[42:43], 0, v[46:47]
	v_lshl_add_u64 v[48:49], v[42:43], 0, v[48:49]
	v_lshl_add_u64 v[50:51], v[42:43], 0, v[50:51]
	v_lshl_add_u64 v[52:53], v[42:43], 0, v[52:53]
	v_lshl_add_u64 v[54:55], v[42:43], 0, v[54:55]
	v_lshl_add_u64 v[56:57], v[42:43], 0, v[56:57]
	v_lshl_add_u64 v[58:59], v[42:43], 0, v[58:59]
	global_load_dword v60, v[44:45], off nt
	global_load_dword v61, v[46:47], off nt
	global_load_dword v62, v[48:49], off nt
	global_load_dword v63, v[50:51], off nt
	global_load_dword v64, v[52:53], off nt
	global_load_dword v65, v[54:55], off nt
	global_load_dword v66, v[56:57], off nt
	global_load_dword v67, v[58:59], off nt
	v_or_b32_e32 v44, 16, v40
	v_mov_b32_e32 v45, v179
	v_or_b32_e32 v46, 18, v40
	v_mov_b32_e32 v47, v179
	v_or_b32_e32 v48, 20, v40
	v_mov_b32_e32 v49, v179
	v_or_b32_e32 v50, 22, v40
	v_mov_b32_e32 v51, v179
	v_or_b32_e32 v52, 24, v40
	v_mov_b32_e32 v53, v179
	v_or_b32_e32 v54, 26, v40
	v_mov_b32_e32 v55, v179
	v_or_b32_e32 v56, 28, v40
	v_mov_b32_e32 v57, v179
	v_or_b32_e32 v58, 30, v40
	v_mov_b32_e32 v59, v179
	v_lshlrev_b64 v[44:45], 12, v[44:45]
	v_lshlrev_b64 v[46:47], 12, v[46:47]
	v_lshlrev_b64 v[48:49], 12, v[48:49]
	v_lshlrev_b64 v[50:51], 12, v[50:51]
	v_lshlrev_b64 v[52:53], 12, v[52:53]
	v_lshlrev_b64 v[54:55], 12, v[54:55]
	v_lshlrev_b64 v[56:57], 12, v[56:57]
	v_lshlrev_b64 v[58:59], 12, v[58:59]
	v_lshl_add_u64 v[44:45], v[42:43], 0, v[44:45]
	v_lshl_add_u64 v[46:47], v[42:43], 0, v[46:47]
	v_lshl_add_u64 v[48:49], v[42:43], 0, v[48:49]
	v_lshl_add_u64 v[50:51], v[42:43], 0, v[50:51]
	v_lshl_add_u64 v[52:53], v[42:43], 0, v[52:53]
	v_lshl_add_u64 v[54:55], v[42:43], 0, v[54:55]
	v_lshl_add_u64 v[56:57], v[42:43], 0, v[56:57]
	v_lshl_add_u64 v[58:59], v[42:43], 0, v[58:59]
	global_load_dword v68, v[44:45], off nt
	global_load_dword v69, v[46:47], off nt
	global_load_dword v70, v[48:49], off nt
	global_load_dword v71, v[50:51], off nt
	global_load_dword v72, v[52:53], off nt
	global_load_dword v73, v[54:55], off nt
	global_load_dword v74, v[56:57], off nt
	global_load_dword v75, v[58:59], off nt
	v_or_b32_e32 v44, 32, v40
	v_mov_b32_e32 v45, v179
	v_or_b32_e32 v46, 34, v40
	v_mov_b32_e32 v47, v179
	v_or_b32_e32 v48, 36, v40
	v_mov_b32_e32 v49, v179
	v_or_b32_e32 v50, 38, v40
	v_mov_b32_e32 v51, v179
	v_or_b32_e32 v52, 40, v40
	v_mov_b32_e32 v53, v179
	v_or_b32_e32 v54, 42, v40
	v_mov_b32_e32 v55, v179
	v_or_b32_e32 v56, 44, v40
	v_mov_b32_e32 v57, v179
	v_or_b32_e32 v58, 46, v40
	v_mov_b32_e32 v59, v179
	v_lshlrev_b64 v[44:45], 12, v[44:45]
	v_lshlrev_b64 v[46:47], 12, v[46:47]
	v_lshlrev_b64 v[48:49], 12, v[48:49]
	v_lshlrev_b64 v[50:51], 12, v[50:51]
	v_lshlrev_b64 v[52:53], 12, v[52:53]
	v_lshlrev_b64 v[54:55], 12, v[54:55]
	v_lshlrev_b64 v[56:57], 12, v[56:57]
	v_lshlrev_b64 v[58:59], 12, v[58:59]
	v_lshl_add_u64 v[44:45], v[42:43], 0, v[44:45]
	v_lshl_add_u64 v[46:47], v[42:43], 0, v[46:47]
	v_lshl_add_u64 v[48:49], v[42:43], 0, v[48:49]
	v_lshl_add_u64 v[50:51], v[42:43], 0, v[50:51]
	v_lshl_add_u64 v[52:53], v[42:43], 0, v[52:53]
	v_lshl_add_u64 v[54:55], v[42:43], 0, v[54:55]
	v_lshl_add_u64 v[56:57], v[42:43], 0, v[56:57]
	v_lshl_add_u64 v[58:59], v[42:43], 0, v[58:59]
	global_load_dword v76, v[44:45], off nt
	global_load_dword v77, v[46:47], off nt
	global_load_dword v78, v[48:49], off nt
	global_load_dword v79, v[50:51], off nt
	global_load_dword v80, v[52:53], off nt
	global_load_dword v81, v[54:55], off nt
	global_load_dword v82, v[56:57], off nt
	s_nop 0
	global_load_dword v58, v[58:59], off nt
	v_or_b32_e32 v44, 48, v40
	v_mov_b32_e32 v45, v179
	v_or_b32_e32 v46, 50, v40
	v_mov_b32_e32 v47, v179
	v_or_b32_e32 v48, 52, v40
	v_mov_b32_e32 v49, v179
	v_or_b32_e32 v50, 54, v40
	v_or_b32_e32 v52, 56, v40
	v_or_b32_e32 v54, 58, v40
	v_or_b32_e32 v56, 60, v40
	v_or_b32_e32 v40, 62, v40
	v_lshlrev_b64 v[44:45], 12, v[44:45]
	v_lshlrev_b64 v[46:47], 12, v[46:47]
	v_lshlrev_b64 v[48:49], 12, v[48:49]
	v_mov_b32_e32 v51, v179
	v_mov_b32_e32 v53, v179
	v_mov_b32_e32 v55, v179
	v_mov_b32_e32 v57, v179
	v_lshlrev_b64 v[40:41], 12, v[40:41]
	v_lshl_add_u64 v[44:45], v[42:43], 0, v[44:45]
	v_lshl_add_u64 v[46:47], v[42:43], 0, v[46:47]
	v_lshl_add_u64 v[48:49], v[42:43], 0, v[48:49]
	v_lshlrev_b64 v[50:51], 12, v[50:51]
	v_lshlrev_b64 v[52:53], 12, v[52:53]
	v_lshlrev_b64 v[54:55], 12, v[54:55]
	v_lshlrev_b64 v[56:57], 12, v[56:57]
	v_lshl_add_u64 v[40:41], v[42:43], 0, v[40:41]
	v_lshl_add_u64 v[50:51], v[42:43], 0, v[50:51]
	v_lshl_add_u64 v[52:53], v[42:43], 0, v[52:53]
	v_lshl_add_u64 v[54:55], v[42:43], 0, v[54:55]
	v_lshl_add_u64 v[56:57], v[42:43], 0, v[56:57]
	global_load_dword v42, v[44:45], off nt
	global_load_dword v43, v[46:47], off nt
	s_nop 0
	global_load_dword v44, v[48:49], off nt
	global_load_dword v45, v[50:51], off nt
	global_load_dword v46, v[52:53], off nt
	global_load_dword v47, v[54:55], off nt
	s_nop 0
	global_load_dword v48, v[56:57], off nt
	s_nop 0
	global_load_dword v40, v[40:41], off nt
	s_waitcnt vmcnt(0)
; __device__ __forceinline__ unsigned pk2(float lo, float hi) { f32v2 v = {lo, hi}; bf16v2 r = __builtin_convertvector(v, bf16v2); return __builtin_bit_cast(unsigned, r); }
; #define LAS __attribute__((address_space(3)))
; #define LDS_WAIT() asm volatile("s_waitcnt lgkmcnt(0)" ::: "memory")
; __device__ __forceinline__ void transpose_item(const float* W, int K, int N, bf16* WT, int k0, int n0, int dst_row0, LAS float* scr, int lane) {
;     ...
; #pragma unroll
;     for (int i = 0; i < 32; ++i) scr[(2 * i + (lane >> 5)) * 33 + (lane & 31)] = wv[i];
;     LDS_WAIT(); asm volatile("" ::: "memory");
;     const int c = lane & 7;
; #pragma unroll
;     for (int j = 0; j < 4; ++j) { const int n = (lane >> 3) + 8 * j; const LAS float* s = scr + (8 * c) * 33 + n;
;         v4u o; o.x = pk2(s[0 * 33], s[1 * 33]); o.y = pk2(s[2 * 33], s[3 * 33]); o.z = pk2(s[4 * 33], s[5 * 33]); o.w = pk2(s[6 * 33], s[7 * 33]);
;         *(v4u*)(WT + (size_t)(dst_row0 + n) * K + k0 + 8 * c) = o; }
;     LDS_WAIT(); asm volatile("" ::: "memory");
	ds_write2_b32 v27, v60, v61 offset1:66
	s_waitcnt vmcnt(28)
	ds_write2_b32 v27, v62, v63 offset0:132 offset1:198
	s_waitcnt vmcnt(26)
	ds_write2_b32 v33, v64, v65 offset0:8 offset1:74
	s_waitcnt vmcnt(24)
	ds_write2_b32 v33, v66, v67 offset0:140 offset1:206
	s_waitcnt vmcnt(22)
	ds_write2_b32 v34, v68, v69 offset0:16 offset1:82
	s_waitcnt vmcnt(20)
	ds_write2_b32 v34, v70, v71 offset0:148 offset1:214
	s_waitcnt vmcnt(18)
	ds_write2_b32 v35, v72, v73 offset0:24 offset1:90
	s_waitcnt vmcnt(16)
	ds_write2_b32 v35, v74, v75 offset0:156 offset1:222
	s_waitcnt vmcnt(14)
	ds_write2_b32 v36, v76, v77 offset0:32 offset1:98
	s_waitcnt vmcnt(12)
	ds_write2_b32 v36, v78, v79 offset0:164 offset1:230
	s_waitcnt vmcnt(10)
	ds_write2_b32 v37, v80, v81 offset0:40 offset1:106
	s_waitcnt vmcnt(8)
	ds_write2_b32 v37, v82, v58 offset0:172 offset1:238
	s_waitcnt vmcnt(6)
	ds_write2_b32 v38, v42, v43 offset0:48 offset1:114
	s_waitcnt vmcnt(4)
	ds_write2_b32 v38, v44, v45 offset0:180 offset1:246
	s_waitcnt vmcnt(2)
	ds_write2_b32 v39, v46, v47 offset0:56 offset1:122
	s_waitcnt vmcnt(0)
	ds_write2_b32 v39, v48, v40 offset0:188 offset1:254
	s_waitcnt lgkmcnt(0)
	ds_read2_b32 v[44:45], v29 offset0:33 offset1:41
	ds_read2_b32 v[46:47], v29 offset1:8
	ds_read2_b32 v[48:49], v29 offset0:66 offset1:74
	ds_read2_b32 v[50:51], v29 offset0:99 offset1:107
	ds_read2_b32 v[52:53], v29 offset0:132 offset1:140
	ds_read2_b32 v[54:55], v29 offset0:165 offset1:173
	ds_read2_b32 v[56:57], v29 offset0:198 offset1:206
	ds_read2_b32 v[58:59], v29 offset0:231 offset1:239
	s_lshl_b32 s94, s5, 1
	s_waitcnt lgkmcnt(6)
	v_cvt_pk_bf16_f32 v40, v46, v44
	v_or_b32_e32 v44, s4, v28
	v_lshl_add_u64 v[60:61], v[10:11], 0, s[94:95]
	v_lshlrev_b32_e32 v62, 11, v44
	v_mov_b32_e32 v63, v179
	s_waitcnt lgkmcnt(4)
	v_cvt_pk_bf16_f32 v41, v48, v50
	s_waitcnt lgkmcnt(2)
	v_cvt_pk_bf16_f32 v42, v52, v54
	s_waitcnt lgkmcnt(0)
	v_cvt_pk_bf16_f32 v43, v56, v58
	v_lshl_add_u64 v[62:63], v[60:61], 0, v[62:63]
	global_store_dwordx4 v[62:63], v[40:43], off sc0 sc1
	v_or_b32_e32 v44, s4, v30
	v_lshlrev_b32_e32 v44, 11, v44
	v_cvt_pk_bf16_f32 v40, v47, v45
	v_cvt_pk_bf16_f32 v41, v49, v51
	v_cvt_pk_bf16_f32 v42, v53, v55
	v_cvt_pk_bf16_f32 v43, v57, v59
	ds_read2_b32 v[46:47], v29 offset0:49 offset1:57
	ds_read2_b32 v[48:49], v29 offset0:16 offset1:24
	ds_read2_b32 v[50:51], v29 offset0:82 offset1:90
	ds_read2_b32 v[52:53], v29 offset0:115 offset1:123
	ds_read2_b32 v[54:55], v29 offset0:148 offset1:156
	ds_read2_b32 v[56:57], v29 offset0:181 offset1:189
	ds_read2_b32 v[58:59], v29 offset0:214 offset1:222
	ds_read2_b32 v[62:63], v29 offset0:247 offset1:255
	v_mov_b32_e32 v45, v179
	v_lshl_add_u64 v[44:45], v[60:61], 0, v[44:45]
	global_store_dwordx4 v[44:45], v[40:43], off sc0 sc1
	v_or_b32_e32 v44, s4, v31
	v_lshlrev_b32_e32 v44, 11, v44
	v_mov_b32_e32 v45, v179
	s_waitcnt lgkmcnt(6)
	v_cvt_pk_bf16_f32 v40, v48, v46
	s_waitcnt lgkmcnt(4)
	v_cvt_pk_bf16_f32 v41, v50, v52
	s_waitcnt lgkmcnt(2)
	v_cvt_pk_bf16_f32 v42, v54, v56
	s_waitcnt lgkmcnt(0)
	v_cvt_pk_bf16_f32 v43, v58, v62
	v_lshl_add_u64 v[44:45], v[60:61], 0, v[44:45]
	global_store_dwordx4 v[44:45], v[40:43], off sc0 sc1
	v_or_b32_e32 v44, s4, v32
	v_lshlrev_b32_e32 v44, 11, v44
	v_mov_b32_e32 v45, v179
	v_cvt_pk_bf16_f32 v40, v49, v47
	v_cvt_pk_bf16_f32 v41, v51, v53
	v_cvt_pk_bf16_f32 v42, v55, v57
	v_cvt_pk_bf16_f32 v43, v59, v63
	v_lshl_add_u64 v[44:45], v[60:61], 0, v[44:45]
	global_store_dwordx4 v[44:45], v[40:43], off sc0 sc1
	s_waitcnt lgkmcnt(0)

; #define LAS __attribute__((address_space(3)))
; __device__ __forceinline__ void transpose_item(const float* W, int K, int N, bf16* WT, int k0, int n0, int dst_row0, LAS float* scr, int lane) {
;     float wv[32];
; #pragma unroll
;     for (int i = 0; i < 32; ++i) wv[i] = __builtin_nontemporal_load(W + (size_t)(k0 + 2 * i + (lane >> 5)) * N + n0 + (lane & 31));
; __device__ __forceinline__ void convert_weights(const Args& A, int l, LAS unsigned char* lds, int gw, int ngw, int wave, int lane) {
;     ...
;         if (r < I_BP) { transpose_item(w_bp, 256, DM, WB + WO_WBP, (r / 32) * 64, (r % 32) * 32, (r % 32) * 32, scr, lane); continue; } r -= I_BP;
;         if (r < I_BP) { transpose_item(w_bg, 256, DM, WB + WO_WBG, (r / 32) * 64, (r % 32) * 32, (r % 32) * 32, scr, lane); continue; } r -= I_BP;
.LBB0_69:
	s_andn2_b64 vcc, exec, s[4:5]
	s_cbranch_vccnz .LBB0_71
	s_add_i32 s4, s23, 0x1500
	s_and_b32 s5, s4, 0x7fffffc0
	s_and_b32 s4, s17, 0x3e0
	v_or_b32_e32 v40, s5, v26
	s_lshl_b32 s94, s4, 2
	v_mov_b32_e32 v41, v179
	v_or_b32_e32 v46, 2, v40
	v_mov_b32_e32 v47, v179
	v_or_b32_e32 v48, 4, v40
	v_mov_b32_e32 v49, v179
	v_or_b32_e32 v50, 6, v40
	v_mov_b32_e32 v51, v179
	v_or_b32_e32 v52, 8, v40
	v_mov_b32_e32 v53, v179
	v_or_b32_e32 v54, 10, v40
	v_mov_b32_e32 v55, v179
	v_or_b32_e32 v56, 12, v40
	v_mov_b32_e32 v57, v179
	v_or_b32_e32 v58, 14, v40
	v_mov_b32_e32 v59, v179
	v_lshl_add_u64 v[42:43], v[12:13], 0, s[94:95]
	v_lshlrev_b64 v[44:45], 12, v[40:41]
	v_lshlrev_b64 v[46:47], 12, v[46:47]
	v_lshlrev_b64 v[48:49], 12, v[48:49]
	v_lshlrev_b64 v[50:51], 12, v[50:51]
	v_lshlrev_b64 v[52:53], 12, v[52:53]
	v_lshlrev_b64 v[54:55], 12, v[54:55]
	v_lshlrev_b64 v[56:57], 12, v[56:57]
	v_lshlrev_b64 v[58:59], 12, v[58:59]
	v_lshl_add_u64 v[44:45], v[42:43], 0, v[44:45]
	v_lshl_add_u64 v[46:47], v[42:43], 0, v[46:47]
	v_lshl_add_u64 v[48:49], v[42:43], 0, v[48:49]
	v_lshl_add_u64 v[50:51], v[42:43], 0, v[50:51]
	v_lshl_add_u64 v[52:53], v[42:43], 0, v[52:53]
	v_lshl_add_u64 v[54:55], v[42:43], 0, v[54:55]
	v_lshl_add_u64 v[56:57], v[42:43], 0, v[56:57]
	v_lshl_add_u64 v[58:59], v[42:43], 0, v[58:59]
	global_load_dword v60, v[44:45], off nt
	global_load_dword v61, v[46:47], off nt
	global_load_dword v62, v[48:49], off nt
	global_load_dword v63, v[50:51], off nt
	global_load_dword v64, v[52:53], off nt
	global_load_dword v65, v[54:55], off nt
	global_load_dword v66, v[56:57], off nt
	global_load_dword v67, v[58:59], off nt
	v_or_b32_e32 v44, 16, v40
	v_mov_b32_e32 v45, v179
	v_or_b32_e32 v46, 18, v40
	v_mov_b32_e32 v47, v179
	v_or_b32_e32 v48, 20, v40
	v_mov_b32_e32 v49, v179
	v_or_b32_e32 v50, 22, v40
	v_mov_b32_e32 v51, v179
	v_or_b32_e32 v52, 24, v40
	v_mov_b32_e32 v53, v179
	v_or_b32_e32 v54, 26, v40
	v_mov_b32_e32 v55, v179
	v_or_b32_e32 v56, 28, v40
	v_mov_b32_e32 v57, v179
	v_or_b32_e32 v58, 30, v40
	v_mov_b32_e32 v59, v179
	v_lshlrev_b64 v[44:45], 12, v[44:45]
	v_lshlrev_b64 v[46:47], 12, v[46:47]
	v_lshlrev_b64 v[48:49], 12, v[48:49]
	v_lshlrev_b64 v[50:51], 12, v[50:51]
	v_lshlrev_b64 v[52:53], 12, v[52:53]
	v_lshlrev_b64 v[54:55], 12, v[54:55]
	v_lshlrev_b64 v[56:57], 12, v[56:57]
	v_lshlrev_b64 v[58:59], 12, v[58:59]
	v_lshl_add_u64 v[44:45], v[42:43], 0, v[44:45]
	v_lshl_add_u64 v[46:47], v[42:43], 0, v[46:47]
	v_lshl_add_u64 v[48:49], v[42:43], 0, v[48:49]
	v_lshl_add_u64 v[50:51], v[42:43], 0, v[50:51]
	v_lshl_add_u64 v[52:53], v[42:43], 0, v[52:53]
	v_lshl_add_u64 v[54:55], v[42:43], 0, v[54:55]
	v_lshl_add_u64 v[56:57], v[42:43], 0, v[56:57]
	v_lshl_add_u64 v[58:59], v[42:43], 0, v[58:59]
	global_load_dword v68, v[44:45], off nt
	global_load_dword v69, v[46:47], off nt
	global_load_dword v70, v[48:49], off nt
	global_load_dword v71, v[50:51], off nt
	global_load_dword v72, v[52:53], off nt
	global_load_dword v73, v[54:55], off nt
	global_load_dword v74, v[56:57], off nt
	global_load_dword v75, v[58:59], off nt
	v_or_b32_e32 v44, 32, v40
	v_mov_b32_e32 v45, v179
	v_or_b32_e32 v46, 34, v40
	v_mov_b32_e32 v47, v179
	v_or_b32_e32 v48, 36, v40
	v_mov_b32_e32 v49, v179
	v_or_b32_e32 v50, 38, v40
	v_mov_b32_e32 v51, v179
	v_or_b32_e32 v52, 40, v40
	v_mov_b32_e32 v53, v179
	v_or_b32_e32 v54, 42, v40
	v_mov_b32_e32 v55, v179
	v_or_b32_e32 v56, 44, v40
	v_mov_b32_e32 v57, v179
	v_or_b32_e32 v58, 46, v40
	v_mov_b32_e32 v59, v179
	v_lshlrev_b64 v[44:45], 12, v[44:45]
	v_lshlrev_b64 v[46:47], 12, v[46:47]
	v_lshlrev_b64 v[48:49], 12, v[48:49]
	v_lshlrev_b64 v[50:51], 12, v[50:51]
	v_lshlrev_b64 v[52:53], 12, v[52:53]
	v_lshlrev_b64 v[54:55], 12, v[54:55]
	v_lshlrev_b64 v[56:57], 12, v[56:57]
	v_lshlrev_b64 v[58:59], 12, v[58:59]
	v_lshl_add_u64 v[44:45], v[42:43], 0, v[44:45]
	v_lshl_add_u64 v[46:47], v[42:43], 0, v[46:47]
	v_lshl_add_u64 v[48:49], v[42:43], 0, v[48:49]
	v_lshl_add_u64 v[50:51], v[42:43], 0, v[50:51]
	v_lshl_add_u64 v[52:53], v[42:43], 0, v[52:53]
	v_lshl_add_u64 v[54:55], v[42:43], 0, v[54:55]
	v_lshl_add_u64 v[56:57], v[42:43], 0, v[56:57]
	v_lshl_add_u64 v[58:59], v[42:43], 0, v[58:59]
	global_load_dword v76, v[44:45], off nt
	global_load_dword v77, v[46:47], off nt
	global_load_dword v78, v[48:49], off nt
	global_load_dword v79, v[50:51], off nt
	global_load_dword v80, v[52:53], off nt
	global_load_dword v81, v[54:55], off nt
	global_load_dword v82, v[56:57], off nt
	s_nop 0
	global_load_dword v58, v[58:59], off nt
	v_or_b32_e32 v44, 48, v40
	v_mov_b32_e32 v45, v179
	v_or_b32_e32 v46, 50, v40
	v_mov_b32_e32 v47, v179
	v_or_b32_e32 v48, 52, v40
	v_mov_b32_e32 v49, v179
	v_or_b32_e32 v50, 54, v40
	v_or_b32_e32 v52, 56, v40
	v_or_b32_e32 v54, 58, v40
	v_or_b32_e32 v56, 60, v40
	v_or_b32_e32 v40, 62, v40
	v_lshlrev_b64 v[44:45], 12, v[44:45]
	v_lshlrev_b64 v[46:47], 12, v[46:47]
	v_lshlrev_b64 v[48:49], 12, v[48:49]
	v_mov_b32_e32 v51, v179
	v_mov_b32_e32 v53, v179
	v_mov_b32_e32 v55, v179
	v_mov_b32_e32 v57, v179
	v_lshlrev_b64 v[40:41], 12, v[40:41]
	v_lshl_add_u64 v[44:45], v[42:43], 0, v[44:45]
	v_lshl_add_u64 v[46:47], v[42:43], 0, v[46:47]
	v_lshl_add_u64 v[48:49], v[42:43], 0, v[48:49]
	v_lshlrev_b64 v[50:51], 12, v[50:51]
	v_lshlrev_b64 v[52:53], 12, v[52:53]
	v_lshlrev_b64 v[54:55], 12, v[54:55]
	v_lshlrev_b64 v[56:57], 12, v[56:57]
	v_lshl_add_u64 v[40:41], v[42:43], 0, v[40:41]
	v_lshl_add_u64 v[50:51], v[42:43], 0, v[50:51]
	v_lshl_add_u64 v[52:53], v[42:43], 0, v[52:53]
	v_lshl_add_u64 v[54:55], v[42:43], 0, v[54:55]
	v_lshl_add_u64 v[56:57], v[42:43], 0, v[56:57]
	global_load_dword v42, v[44:45], off nt
	global_load_dword v43, v[46:47], off nt
	s_nop 0
	global_load_dword v44, v[48:49], off nt
	global_load_dword v45, v[50:51], off nt
	global_load_dword v46, v[52:53], off nt
	global_load_dword v47, v[54:55], off nt
	s_nop 0
	global_load_dword v48, v[56:57], off nt
	s_nop 0
	global_load_dword v40, v[40:41], off nt
	s_waitcnt vmcnt(0)
; __device__ __forceinline__ unsigned pk2(float lo, float hi) { f32v2 v = {lo, hi}; bf16v2 r = __builtin_convertvector(v, bf16v2); return __builtin_bit_cast(unsigned, r); }
; #define LAS __attribute__((address_space(3)))
; #define LDS_WAIT() asm volatile("s_waitcnt lgkmcnt(0)" ::: "memory")
; __device__ __forceinline__ void transpose_item(const float* W, int K, int N, bf16* WT, int k0, int n0, int dst_row0, LAS float* scr, int lane) {
;     ...
; #pragma unroll
;     for (int i = 0; i < 32; ++i) scr[(2 * i + (lane >> 5)) * 33 + (lane & 31)] = wv[i];
;     LDS_WAIT(); asm volatile("" ::: "memory");
;     const int c = lane & 7;
; #pragma unroll
;     for (int j = 0; j < 4; ++j) { const int n = (lane >> 3) + 8 * j; const LAS float* s = scr + (8 * c) * 33 + n;
;         v4u o; o.x = pk2(s[0 * 33], s[1 * 33]); o.y = pk2(s[2 * 33], s[3 * 33]); o.z = pk2(s[4 * 33], s[5 * 33]); o.w = pk2(s[6 * 33], s[7 * 33]);
;         *(v4u*)(WT + (size_t)(dst_row0 + n) * K + k0 + 8 * c) = o; }
;     LDS_WAIT(); asm volatile("" ::: "memory");
	ds_write2_b32 v27, v60, v61 offset1:66
	s_waitcnt vmcnt(28)
	ds_write2_b32 v27, v62, v63 offset0:132 offset1:198
	s_waitcnt vmcnt(26)
	ds_write2_b32 v33, v64, v65 offset0:8 offset1:74
	s_waitcnt vmcnt(24)
	ds_write2_b32 v33, v66, v67 offset0:140 offset1:206
	s_waitcnt vmcnt(22)
	ds_write2_b32 v34, v68, v69 offset0:16 offset1:82
	s_waitcnt vmcnt(20)
	ds_write2_b32 v34, v70, v71 offset0:148 offset1:214
	s_waitcnt vmcnt(18)
	ds_write2_b32 v35, v72, v73 offset0:24 offset1:90
	s_waitcnt vmcnt(16)
	ds_write2_b32 v35, v74, v75 offset0:156 offset1:222
	s_waitcnt vmcnt(14)
	ds_write2_b32 v36, v76, v77 offset0:32 offset1:98
	s_waitcnt vmcnt(12)
	ds_write2_b32 v36, v78, v79 offset0:164 offset1:230
	s_waitcnt vmcnt(10)
	ds_write2_b32 v37, v80, v81 offset0:40 offset1:106
	s_waitcnt vmcnt(8)
	ds_write2_b32 v37, v82, v58 offset0:172 offset1:238
	s_waitcnt vmcnt(6)
	ds_write2_b32 v38, v42, v43 offset0:48 offset1:114
	s_waitcnt vmcnt(4)
	ds_write2_b32 v38, v44, v45 offset0:180 offset1:246
	s_waitcnt vmcnt(2)
	ds_write2_b32 v39, v46, v47 offset0:56 offset1:122
	s_waitcnt vmcnt(0)
	ds_write2_b32 v39, v48, v40 offset0:188 offset1:254
	s_waitcnt lgkmcnt(0)
	ds_read2_b32 v[44:45], v29 offset0:33 offset1:41
	ds_read2_b32 v[46:47], v29 offset1:8
	ds_read2_b32 v[48:49], v29 offset0:66 offset1:74
	ds_read2_b32 v[50:51], v29 offset0:99 offset1:107
	ds_read2_b32 v[52:53], v29 offset0:132 offset1:140
	ds_read2_b32 v[54:55], v29 offset0:165 offset1:173
	ds_read2_b32 v[56:57], v29 offset0:198 offset1:206
	ds_read2_b32 v[58:59], v29 offset0:231 offset1:239
	s_lshl_b32 s94, s5, 1
	s_waitcnt lgkmcnt(6)
	v_cvt_pk_bf16_f32 v40, v46, v44
	v_or_b32_e32 v44, s4, v28
	v_lshl_add_u64 v[60:61], v[14:15], 0, s[94:95]
	v_lshlrev_b32_e32 v62, 9, v44
	v_mov_b32_e32 v63, v179
	s_waitcnt lgkmcnt(4)
	v_cvt_pk_bf16_f32 v41, v48, v50
	s_waitcnt lgkmcnt(2)
	v_cvt_pk_bf16_f32 v42, v52, v54
	s_waitcnt lgkmcnt(0)
	v_cvt_pk_bf16_f32 v43, v56, v58
	v_lshl_add_u64 v[62:63], v[60:61], 0, v[62:63]
	global_store_dwordx4 v[62:63], v[40:43], off sc0 sc1
	v_or_b32_e32 v44, s4, v30
	v_lshlrev_b32_e32 v44, 9, v44
	v_cvt_pk_bf16_f32 v40, v47, v45
	v_cvt_pk_bf16_f32 v41, v49, v51
	v_cvt_pk_bf16_f32 v42, v53, v55
	v_cvt_pk_bf16_f32 v43, v57, v59
	ds_read2_b32 v[46:47], v29 offset0:49 offset1:57
	ds_read2_b32 v[48:49], v29 offset0:16 offset1:24
	ds_read2_b32 v[50:51], v29 offset0:82 offset1:90
	ds_read2_b32 v[52:53], v29 offset0:115 offset1:123
	ds_read2_b32 v[54:55], v29 offset0:148 offset1:156
	ds_read2_b32 v[56:57], v29 offset0:181 offset1:189
	ds_read2_b32 v[58:59], v29 offset0:214 offset1:222
	ds_read2_b32 v[62:63], v29 offset0:247 offset1:255
	v_mov_b32_e32 v45, v179
	v_lshl_add_u64 v[44:45], v[60:61], 0, v[44:45]
	global_store_dwordx4 v[44:45], v[40:43], off sc0 sc1
	v_or_b32_e32 v44, s4, v31
	v_lshlrev_b32_e32 v44, 9, v44
	v_mov_b32_e32 v45, v179
	s_waitcnt lgkmcnt(6)
	v_cvt_pk_bf16_f32 v40, v48, v46
	s_waitcnt lgkmcnt(4)
	v_cvt_pk_bf16_f32 v41, v50, v52
	s_waitcnt lgkmcnt(2)
	v_cvt_pk_bf16_f32 v42, v54, v56
	s_waitcnt lgkmcnt(0)
	v_cvt_pk_bf16_f32 v43, v58, v62
	v_lshl_add_u64 v[44:45], v[60:61], 0, v[44:45]
	global_store_dwordx4 v[44:45], v[40:43], off sc0 sc1
	v_or_b32_e32 v44, s4, v32
	v_lshlrev_b32_e32 v44, 9, v44
	v_mov_b32_e32 v45, v179
	v_cvt_pk_bf16_f32 v40, v49, v47
	v_cvt_pk_bf16_f32 v41, v51, v53
	v_cvt_pk_bf16_f32 v42, v55, v57
	v_cvt_pk_bf16_f32 v43, v59, v63
	v_lshl_add_u64 v[44:45], v[60:61], 0, v[44:45]
	global_store_dwordx4 v[44:45], v[40:43], off sc0 sc1
	s_waitcnt lgkmcnt(0)

; #define LAS __attribute__((address_space(3)))
; __device__ __forceinline__ void transpose_item(const float* W, int K, int N, bf16* WT, int k0, int n0, int dst_row0, LAS float* scr, int lane) {
;     float wv[32];
; #pragma unroll
;     for (int i = 0; i < 32; ++i) wv[i] = __builtin_nontemporal_load(W + (size_t)(k0 + 2 * i + (lane >> 5)) * N + n0 + (lane & 31));
; __device__ __forceinline__ void convert_weights(const Args& A, int l, LAS unsigned char* lds, int gw, int ngw, int wave, int lane) {
;     ...
;         if (r < I_BP) { transpose_item(w_bp, 256, DM, WB + WO_WBP, (r / 32) * 64, (r % 32) * 32, (r % 32) * 32, scr, lane); continue; } r -= I_BP;
;         if (r < I_BP) { transpose_item(w_bg, 256, DM, WB + WO_WBG, (r / 32) * 64, (r % 32) * 32, (r % 32) * 32, scr, lane); continue; } r -= I_BP;
.LBB0_72:
	s_andn2_b64 vcc, exec, s[4:5]
	s_cbranch_vccnz .LBB0_74
	s_add_i32 s4, s23, 0x1600
	s_and_b32 s5, s4, 0x7fffffc0
	s_and_b32 s4, s17, 0x3e0
	v_or_b32_e32 v40, s5, v26
	s_lshl_b32 s94, s4, 2
	v_mov_b32_e32 v41, v179
	v_or_b32_e32 v46, 2, v40
	v_mov_b32_e32 v47, v179
	v_or_b32_e32 v48, 4, v40
	v_mov_b32_e32 v49, v179
	v_or_b32_e32 v50, 6, v40
	v_mov_b32_e32 v51, v179
	v_or_b32_e32 v52, 8, v40
	v_mov_b32_e32 v53, v179
	v_or_b32_e32 v54, 10, v40
	v_mov_b32_e32 v55, v179
	v_or_b32_e32 v56, 12, v40
	v_mov_b32_e32 v57, v179
	v_or_b32_e32 v58, 14, v40
	v_mov_b32_e32 v59, v179
	v_lshl_add_u64 v[42:43], v[16:17], 0, s[94:95]
	v_lshlrev_b64 v[44:45], 12, v[40:41]
	v_lshlrev_b64 v[46:47], 12, v[46:47]
	v_lshlrev_b64 v[48:49], 12, v[48:49]
	v_lshlrev_b64 v[50:51], 12, v[50:51]
	v_lshlrev_b64 v[52:53], 12, v[52:53]
	v_lshlrev_b64 v[54:55], 12, v[54:55]
	v_lshlrev_b64 v[56:57], 12, v[56:57]
	v_lshlrev_b64 v[58:59], 12, v[58:59]
	v_lshl_add_u64 v[44:45], v[42:43], 0, v[44:45]
	v_lshl_add_u64 v[46:47], v[42:43], 0, v[46:47]
	v_lshl_add_u64 v[48:49], v[42:43], 0, v[48:49]
	v_lshl_add_u64 v[50:51], v[42:43], 0, v[50:51]
	v_lshl_add_u64 v[52:53], v[42:43], 0, v[52:53]
	v_lshl_add_u64 v[54:55], v[42:43], 0, v[54:55]
	v_lshl_add_u64 v[56:57], v[42:43], 0, v[56:57]
	v_lshl_add_u64 v[58:59], v[42:43], 0, v[58:59]
	global_load_dword v60, v[44:45], off nt
	global_load_dword v61, v[46:47], off nt
	global_load_dword v62, v[48:49], off nt
	global_load_dword v63, v[50:51], off nt
	global_load_dword v64, v[52:53], off nt
	global_load_dword v65, v[54:55], off nt
	global_load_dword v66, v[56:57], off nt
	global_load_dword v67, v[58:59], off nt
	v_or_b32_e32 v44, 16, v40
	v_mov_b32_e32 v45, v179
	v_or_b32_e32 v46, 18, v40
	v_mov_b32_e32 v47, v179
	v_or_b32_e32 v48, 20, v40
	v_mov_b32_e32 v49, v179
	v_or_b32_e32 v50, 22, v40
	v_mov_b32_e32 v51, v179
	v_or_b32_e32 v52, 24, v40
	v_mov_b32_e32 v53, v179
	v_or_b32_e32 v54, 26, v40
	v_mov_b32_e32 v55, v179
	v_or_b32_e32 v56, 28, v40
	v_mov_b32_e32 v57, v179
	v_or_b32_e32 v58, 30, v40
	v_mov_b32_e32 v59, v179
	v_lshlrev_b64 v[44:45], 12, v[44:45]
	v_lshlrev_b64 v[46:47], 12, v[46:47]
	v_lshlrev_b64 v[48:49], 12, v[48:49]
	v_lshlrev_b64 v[50:51], 12, v[50:51]
	v_lshlrev_b64 v[52:53], 12, v[52:53]
	v_lshlrev_b64 v[54:55], 12, v[54:55]
	v_lshlrev_b64 v[56:57], 12, v[56:57]
	v_lshlrev_b64 v[58:59], 12, v[58:59]
	v_lshl_add_u64 v[44:45], v[42:43], 0, v[44:45]
	v_lshl_add_u64 v[46:47], v[42:43], 0, v[46:47]
	v_lshl_add_u64 v[48:49], v[42:43], 0, v[48:49]
	v_lshl_add_u64 v[50:51], v[42:43], 0, v[50:51]
	v_lshl_add_u64 v[52:53], v[42:43], 0, v[52:53]
	v_lshl_add_u64 v[54:55], v[42:43], 0, v[54:55]
	v_lshl_add_u64 v[56:57], v[42:43], 0, v[56:57]
	v_lshl_add_u64 v[58:59], v[42:43], 0, v[58:59]
	global_load_dword v68, v[44:45], off nt
	global_load_dword v69, v[46:47], off nt
	global_load_dword v70, v[48:49], off nt
	global_load_dword v71, v[50:51], off nt
	global_load_dword v72, v[52:53], off nt
	global_load_dword v73, v[54:55], off nt
	global_load_dword v74, v[56:57], off nt
	global_load_dword v75, v[58:59], off nt
	v_or_b32_e32 v44, 32, v40
	v_mov_b32_e32 v45, v179
	v_or_b32_e32 v46, 34, v40
	v_mov_b32_e32 v47, v179
	v_or_b32_e32 v48, 36, v40
	v_mov_b32_e32 v49, v179
	v_or_b32_e32 v50, 38, v40
	v_mov_b32_e32 v51, v179
	v_or_b32_e32 v52, 40, v40
	v_mov_b32_e32 v53, v179
	v_or_b32_e32 v54, 42, v40
	v_mov_b32_e32 v55, v179
	v_or_b32_e32 v56, 44, v40
	v_mov_b32_e32 v57, v179
	v_or_b32_e32 v58, 46, v40
	v_mov_b32_e32 v59, v179
	v_lshlrev_b64 v[44:45], 12, v[44:45]
	v_lshlrev_b64 v[46:47], 12, v[46:47]
	v_lshlrev_b64 v[48:49], 12, v[48:49]
	v_lshlrev_b64 v[50:51], 12, v[50:51]
	v_lshlrev_b64 v[52:53], 12, v[52:53]
	v_lshlrev_b64 v[54:55], 12, v[54:55]
	v_lshlrev_b64 v[56:57], 12, v[56:57]
	v_lshlrev_b64 v[58:59], 12, v[58:59]
	v_lshl_add_u64 v[44:45], v[42:43], 0, v[44:45]
	v_lshl_add_u64 v[46:47], v[42:43], 0, v[46:47]
	v_lshl_add_u64 v[48:49], v[42:43], 0, v[48:49]
	v_lshl_add_u64 v[50:51], v[42:43], 0, v[50:51]
	v_lshl_add_u64 v[52:53], v[42:43], 0, v[52:53]
	v_lshl_add_u64 v[54:55], v[42:43], 0, v[54:55]
	v_lshl_add_u64 v[56:57], v[42:43], 0, v[56:57]
	v_lshl_add_u64 v[58:59], v[42:43], 0, v[58:59]
	global_load_dword v76, v[44:45], off nt
	global_load_dword v77, v[46:47], off nt
	global_load_dword v78, v[48:49], off nt
	global_load_dword v79, v[50:51], off nt
	global_load_dword v80, v[52:53], off nt
	global_load_dword v81, v[54:55], off nt
	global_load_dword v82, v[56:57], off nt
	s_nop 0
	global_load_dword v58, v[58:59], off nt
	v_or_b32_e32 v44, 48, v40
	v_mov_b32_e32 v45, v179
	v_or_b32_e32 v46, 50, v40
	v_mov_b32_e32 v47, v179
	v_or_b32_e32 v48, 52, v40
	v_mov_b32_e32 v49, v179
	v_or_b32_e32 v50, 54, v40
	v_or_b32_e32 v52, 56, v40
	v_or_b32_e32 v54, 58, v40
	v_or_b32_e32 v56, 60, v40
	v_or_b32_e32 v40, 62, v40
	v_lshlrev_b64 v[44:45], 12, v[44:45]
	v_lshlrev_b64 v[46:47], 12, v[46:47]
	v_lshlrev_b64 v[48:49], 12, v[48:49]
	v_mov_b32_e32 v51, v179
	v_mov_b32_e32 v53, v179
	v_mov_b32_e32 v55, v179
	v_mov_b32_e32 v57, v179
	v_lshlrev_b64 v[40:41], 12, v[40:41]
	v_lshl_add_u64 v[44:45], v[42:43], 0, v[44:45]
	v_lshl_add_u64 v[46:47], v[42:43], 0, v[46:47]
	v_lshl_add_u64 v[48:49], v[42:43], 0, v[48:49]
	v_lshlrev_b64 v[50:51], 12, v[50:51]
	v_lshlrev_b64 v[52:53], 12, v[52:53]
	v_lshlrev_b64 v[54:55], 12, v[54:55]
	v_lshlrev_b64 v[56:57], 12, v[56:57]
	v_lshl_add_u64 v[40:41], v[42:43], 0, v[40:41]
	v_lshl_add_u64 v[50:51], v[42:43], 0, v[50:51]
	v_lshl_add_u64 v[52:53], v[42:43], 0, v[52:53]
	v_lshl_add_u64 v[54:55], v[42:43], 0, v[54:55]
	v_lshl_add_u64 v[56:57], v[42:43], 0, v[56:57]
	global_load_dword v42, v[44:45], off nt
	global_load_dword v43, v[46:47], off nt
	s_nop 0
	global_load_dword v44, v[48:49], off nt
	global_load_dword v45, v[50:51], off nt
	global_load_dword v46, v[52:53], off nt
	global_load_dword v47, v[54:55], off nt
	s_nop 0
	global_load_dword v48, v[56:57], off nt
	s_nop 0
	global_load_dword v40, v[40:41], off nt
	s_waitcnt vmcnt(0)
; __device__ __forceinline__ unsigned pk2(float lo, float hi) { f32v2 v = {lo, hi}; bf16v2 r = __builtin_convertvector(v, bf16v2); return __builtin_bit_cast(unsigned, r); }
; #define LAS __attribute__((address_space(3)))
; #define LDS_WAIT() asm volatile("s_waitcnt lgkmcnt(0)" ::: "memory")
; __device__ __forceinline__ void transpose_item(const float* W, int K, int N, bf16* WT, int k0, int n0, int dst_row0, LAS float* scr, int lane) {
;     ...
; #pragma unroll
;     for (int i = 0; i < 32; ++i) scr[(2 * i + (lane >> 5)) * 33 + (lane & 31)] = wv[i];
;     LDS_WAIT(); asm volatile("" ::: "memory");
;     const int c = lane & 7;
; #pragma unroll
;     for (int j = 0; j < 4; ++j) { const int n = (lane >> 3) + 8 * j; const LAS float* s = scr + (8 * c) * 33 + n;
;         v4u o; o.x = pk2(s[0 * 33], s[1 * 33]); o.y = pk2(s[2 * 33], s[3 * 33]); o.z = pk2(s[4 * 33], s[5 * 33]); o.w = pk2(s[6 * 33], s[7 * 33]);
;         *(v4u*)(WT + (size_t)(dst_row0 + n) * K + k0 + 8 * c) = o; }
;     LDS_WAIT(); asm volatile("" ::: "memory");
	ds_write2_b32 v27, v60, v61 offset1:66
	s_waitcnt vmcnt(28)
	ds_write2_b32 v27, v62, v63 offset0:132 offset1:198
	s_waitcnt vmcnt(26)
	ds_write2_b32 v33, v64, v65 offset0:8 offset1:74
	s_waitcnt vmcnt(24)
	ds_write2_b32 v33, v66, v67 offset0:140 offset1:206
	s_waitcnt vmcnt(22)
	ds_write2_b32 v34, v68, v69 offset0:16 offset1:82
	s_waitcnt vmcnt(20)
	ds_write2_b32 v34, v70, v71 offset0:148 offset1:214
	s_waitcnt vmcnt(18)
	ds_write2_b32 v35, v72, v73 offset0:24 offset1:90
	s_waitcnt vmcnt(16)
	ds_write2_b32 v35, v74, v75 offset0:156 offset1:222
	s_waitcnt vmcnt(14)
	ds_write2_b32 v36, v76, v77 offset0:32 offset1:98
	s_waitcnt vmcnt(12)
	ds_write2_b32 v36, v78, v79 offset0:164 offset1:230
	s_waitcnt vmcnt(10)
	ds_write2_b32 v37, v80, v81 offset0:40 offset1:106
	s_waitcnt vmcnt(8)
	ds_write2_b32 v37, v82, v58 offset0:172 offset1:238
	s_waitcnt vmcnt(6)
	ds_write2_b32 v38, v42, v43 offset0:48 offset1:114
	s_waitcnt vmcnt(4)
	ds_write2_b32 v38, v44, v45 offset0:180 offset1:246
	s_waitcnt vmcnt(2)
	ds_write2_b32 v39, v46, v47 offset0:56 offset1:122
	s_waitcnt vmcnt(0)
	ds_write2_b32 v39, v48, v40 offset0:188 offset1:254
	s_waitcnt lgkmcnt(0)
	ds_read2_b32 v[44:45], v29 offset0:33 offset1:41
	ds_read2_b32 v[46:47], v29 offset1:8
	ds_read2_b32 v[48:49], v29 offset0:66 offset1:74
	ds_read2_b32 v[50:51], v29 offset0:99 offset1:107
	ds_read2_b32 v[52:53], v29 offset0:132 offset1:140
	ds_read2_b32 v[54:55], v29 offset0:165 offset1:173
	ds_read2_b32 v[56:57], v29 offset0:198 offset1:206
	ds_read2_b32 v[58:59], v29 offset0:231 offset1:239
	s_lshl_b32 s94, s5, 1
	s_waitcnt lgkmcnt(6)
	v_cvt_pk_bf16_f32 v40, v46, v44
	v_or_b32_e32 v44, s4, v28
	v_lshl_add_u64 v[60:61], v[18:19], 0, s[94:95]
	v_lshlrev_b32_e32 v62, 9, v44
	v_mov_b32_e32 v63, v179
	s_waitcnt lgkmcnt(4)
	v_cvt_pk_bf16_f32 v41, v48, v50
	s_waitcnt lgkmcnt(2)
	v_cvt_pk_bf16_f32 v42, v52, v54
	s_waitcnt lgkmcnt(0)
	v_cvt_pk_bf16_f32 v43, v56, v58
	v_lshl_add_u64 v[62:63], v[60:61], 0, v[62:63]
	global_store_dwordx4 v[62:63], v[40:43], off sc0 sc1
	v_or_b32_e32 v44, s4, v30
	v_lshlrev_b32_e32 v44, 9, v44
	v_cvt_pk_bf16_f32 v40, v47, v45
	v_cvt_pk_bf16_f32 v41, v49, v51
	v_cvt_pk_bf16_f32 v42, v53, v55
	v_cvt_pk_bf16_f32 v43, v57, v59
	ds_read2_b32 v[46:47], v29 offset0:49 offset1:57
	ds_read2_b32 v[48:49], v29 offset0:16 offset1:24
	ds_read2_b32 v[50:51], v29 offset0:82 offset1:90
	ds_read2_b32 v[52:53], v29 offset0:115 offset1:123
	ds_read2_b32 v[54:55], v29 offset0:148 offset1:156
	ds_read2_b32 v[56:57], v29 offset0:181 offset1:189
	ds_read2_b32 v[58:59], v29 offset0:214 offset1:222
	ds_read2_b32 v[62:63], v29 offset0:247 offset1:255
	v_mov_b32_e32 v45, v179
	v_lshl_add_u64 v[44:45], v[60:61], 0, v[44:45]
	global_store_dwordx4 v[44:45], v[40:43], off sc0 sc1
	v_or_b32_e32 v44, s4, v31
	v_lshlrev_b32_e32 v44, 9, v44
	v_mov_b32_e32 v45, v179
	s_waitcnt lgkmcnt(6)
	v_cvt_pk_bf16_f32 v40, v48, v46
	s_waitcnt lgkmcnt(4)
	v_cvt_pk_bf16_f32 v41, v50, v52
	s_waitcnt lgkmcnt(2)
	v_cvt_pk_bf16_f32 v42, v54, v56
	s_waitcnt lgkmcnt(0)
	v_cvt_pk_bf16_f32 v43, v58, v62
	v_lshl_add_u64 v[44:45], v[60:61], 0, v[44:45]
	global_store_dwordx4 v[44:45], v[40:43], off sc0 sc1
	v_or_b32_e32 v44, s4, v32
	v_lshlrev_b32_e32 v44, 9, v44
	v_mov_b32_e32 v45, v179
	v_cvt_pk_bf16_f32 v40, v49, v47
	v_cvt_pk_bf16_f32 v41, v51, v53
	v_cvt_pk_bf16_f32 v42, v55, v57
	v_cvt_pk_bf16_f32 v43, v59, v63
	v_lshl_add_u64 v[44:45], v[60:61], 0, v[44:45]
	global_store_dwordx4 v[44:45], v[40:43], off sc0 sc1
	s_waitcnt lgkmcnt(0)

; #define LAS __attribute__((address_space(3)))
; __device__ __forceinline__ void transpose_item(const float* W, int K, int N, bf16* WT, int k0, int n0, int dst_row0, LAS float* scr, int lane) {
;     float wv[32];
; #pragma unroll
;     for (int i = 0; i < 32; ++i) wv[i] = __builtin_nontemporal_load(W + (size_t)(k0 + 2 * i + (lane >> 5)) * N + n0 + (lane & 31));
; __device__ __forceinline__ void convert_weights(const Args& A, int l, LAS unsigned char* lds, int gw, int ngw, int wave, int lane) {
;     ...
;         if (r < I_BS) { transpose_item(w_bs, 512, DM, WB + WO_WBS, (r / 32) * 64, (r % 32) * 32, (r % 32) * 32, scr, lane); continue; } r -= I_BS;
.LBB0_75:
	s_andn2_b64 vcc, exec, s[4:5]
	s_cbranch_vccnz .LBB0_77
	s_add_i32 s4, s23, 0x1800
	s_and_b32 s5, s4, 0x7fffffc0
	s_and_b32 s4, s17, 0x3e0
	v_or_b32_e32 v40, s5, v26
	s_lshl_b32 s94, s4, 2
	v_mov_b32_e32 v41, v179
	v_or_b32_e32 v46, 2, v40
	v_mov_b32_e32 v47, v179
	v_or_b32_e32 v48, 4, v40
	v_mov_b32_e32 v49, v179
	v_or_b32_e32 v50, 6, v40
	v_mov_b32_e32 v51, v179
	v_or_b32_e32 v52, 8, v40
	v_mov_b32_e32 v53, v179
	v_or_b32_e32 v54, 10, v40
	v_mov_b32_e32 v55, v179
	v_or_b32_e32 v56, 12, v40
	v_mov_b32_e32 v57, v179
	v_or_b32_e32 v58, 14, v40
	v_mov_b32_e32 v59, v179
	v_lshl_add_u64 v[42:43], v[20:21], 0, s[94:95]
	v_lshlrev_b64 v[44:45], 12, v[40:41]
	v_lshlrev_b64 v[46:47], 12, v[46:47]
	v_lshlrev_b64 v[48:49], 12, v[48:49]
	v_lshlrev_b64 v[50:51], 12, v[50:51]
	v_lshlrev_b64 v[52:53], 12, v[52:53]
	v_lshlrev_b64 v[54:55], 12, v[54:55]
	v_lshlrev_b64 v[56:57], 12, v[56:57]
	v_lshlrev_b64 v[58:59], 12, v[58:59]
	v_lshl_add_u64 v[44:45], v[42:43], 0, v[44:45]
	v_lshl_add_u64 v[46:47], v[42:43], 0, v[46:47]
	v_lshl_add_u64 v[48:49], v[42:43], 0, v[48:49]
	v_lshl_add_u64 v[50:51], v[42:43], 0, v[50:51]
	v_lshl_add_u64 v[52:53], v[42:43], 0, v[52:53]
	v_lshl_add_u64 v[54:55], v[42:43], 0, v[54:55]
	v_lshl_add_u64 v[56:57], v[42:43], 0, v[56:57]
	v_lshl_add_u64 v[58:59], v[42:43], 0, v[58:59]
	global_load_dword v60, v[44:45], off nt
	global_load_dword v61, v[46:47], off nt
	global_load_dword v62, v[48:49], off nt
	global_load_dword v63, v[50:51], off nt
	global_load_dword v64, v[52:53], off nt
	global_load_dword v65, v[54:55], off nt
	global_load_dword v66, v[56:57], off nt
	global_load_dword v67, v[58:59], off nt
	v_or_b32_e32 v44, 16, v40
	v_mov_b32_e32 v45, v179
	v_or_b32_e32 v46, 18, v40
	v_mov_b32_e32 v47, v179
	v_or_b32_e32 v48, 20, v40
	v_mov_b32_e32 v49, v179
	v_or_b32_e32 v50, 22, v40
	v_mov_b32_e32 v51, v179
	v_or_b32_e32 v52, 24, v40
	v_mov_b32_e32 v53, v179
	v_or_b32_e32 v54, 26, v40
	v_mov_b32_e32 v55, v179
	v_or_b32_e32 v56, 28, v40
	v_mov_b32_e32 v57, v179
	v_or_b32_e32 v58, 30, v40
	v_mov_b32_e32 v59, v179
	v_lshlrev_b64 v[44:45], 12, v[44:45]
	v_lshlrev_b64 v[46:47], 12, v[46:47]
	v_lshlrev_b64 v[48:49], 12, v[48:49]
	v_lshlrev_b64 v[50:51], 12, v[50:51]
	v_lshlrev_b64 v[52:53], 12, v[52:53]
	v_lshlrev_b64 v[54:55], 12, v[54:55]
	v_lshlrev_b64 v[56:57], 12, v[56:57]
	v_lshlrev_b64 v[58:59], 12, v[58:59]
	v_lshl_add_u64 v[44:45], v[42:43], 0, v[44:45]
	v_lshl_add_u64 v[46:47], v[42:43], 0, v[46:47]
	v_lshl_add_u64 v[48:49], v[42:43], 0, v[48:49]
	v_lshl_add_u64 v[50:51], v[42:43], 0, v[50:51]
	v_lshl_add_u64 v[52:53], v[42:43], 0, v[52:53]
	v_lshl_add_u64 v[54:55], v[42:43], 0, v[54:55]
	v_lshl_add_u64 v[56:57], v[42:43], 0, v[56:57]
	v_lshl_add_u64 v[58:59], v[42:43], 0, v[58:59]
	global_load_dword v68, v[44:45], off nt
	global_load_dword v69, v[46:47], off nt
	global_load_dword v70, v[48:49], off nt
	global_load_dword v71, v[50:51], off nt
	global_load_dword v72, v[52:53], off nt
	global_load_dword v73, v[54:55], off nt
	global_load_dword v74, v[56:57], off nt
	global_load_dword v75, v[58:59], off nt
	v_or_b32_e32 v44, 32, v40
	v_mov_b32_e32 v45, v179
	v_or_b32_e32 v46, 34, v40
	v_mov_b32_e32 v47, v179
	v_or_b32_e32 v48, 36, v40
	v_mov_b32_e32 v49, v179
	v_or_b32_e32 v50, 38, v40
	v_mov_b32_e32 v51, v179
	v_or_b32_e32 v52, 40, v40
	v_mov_b32_e32 v53, v179
	v_or_b32_e32 v54, 42, v40
	v_mov_b32_e32 v55, v179
	v_or_b32_e32 v56, 44, v40
	v_mov_b32_e32 v57, v179
	v_or_b32_e32 v58, 46, v40
	v_mov_b32_e32 v59, v179
	v_lshlrev_b64 v[44:45], 12, v[44:45]
	v_lshlrev_b64 v[46:47], 12, v[46:47]
	v_lshlrev_b64 v[48:49], 12, v[48:49]
	v_lshlrev_b64 v[50:51], 12, v[50:51]
	v_lshlrev_b64 v[52:53], 12, v[52:53]
	v_lshlrev_b64 v[54:55], 12, v[54:55]
	v_lshlrev_b64 v[56:57], 12, v[56:57]
	v_lshlrev_b64 v[58:59], 12, v[58:59]
	v_lshl_add_u64 v[44:45], v[42:43], 0, v[44:45]
	v_lshl_add_u64 v[46:47], v[42:43], 0, v[46:47]
	v_lshl_add_u64 v[48:49], v[42:43], 0, v[48:49]
	v_lshl_add_u64 v[50:51], v[42:43], 0, v[50:51]
	v_lshl_add_u64 v[52:53], v[42:43], 0, v[52:53]
	v_lshl_add_u64 v[54:55], v[42:43], 0, v[54:55]
	v_lshl_add_u64 v[56:57], v[42:43], 0, v[56:57]
	v_lshl_add_u64 v[58:59], v[42:43], 0, v[58:59]
	global_load_dword v76, v[44:45], off nt
	global_load_dword v77, v[46:47], off nt
	global_load_dword v78, v[48:49], off nt
	global_load_dword v79, v[50:51], off nt
	global_load_dword v80, v[52:53], off nt
	global_load_dword v81, v[54:55], off nt
	global_load_dword v82, v[56:57], off nt
	s_nop 0
	global_load_dword v58, v[58:59], off nt
	v_or_b32_e32 v44, 48, v40
	v_mov_b32_e32 v45, v179
	v_or_b32_e32 v46, 50, v40
	v_mov_b32_e32 v47, v179
	v_or_b32_e32 v48, 52, v40
	v_mov_b32_e32 v49, v179
	v_or_b32_e32 v50, 54, v40
	v_or_b32_e32 v52, 56, v40
	v_or_b32_e32 v54, 58, v40
	v_or_b32_e32 v56, 60, v40
	v_or_b32_e32 v40, 62, v40
	v_lshlrev_b64 v[44:45], 12, v[44:45]
	v_lshlrev_b64 v[46:47], 12, v[46:47]
	v_lshlrev_b64 v[48:49], 12, v[48:49]
	v_mov_b32_e32 v51, v179
	v_mov_b32_e32 v53, v179
	v_mov_b32_e32 v55, v179
	v_mov_b32_e32 v57, v179
	v_lshlrev_b64 v[40:41], 12, v[40:41]
	v_lshl_add_u64 v[44:45], v[42:43], 0, v[44:45]
	v_lshl_add_u64 v[46:47], v[42:43], 0, v[46:47]
	v_lshl_add_u64 v[48:49], v[42:43], 0, v[48:49]
	v_lshlrev_b64 v[50:51], 12, v[50:51]
	v_lshlrev_b64 v[52:53], 12, v[52:53]
	v_lshlrev_b64 v[54:55], 12, v[54:55]
	v_lshlrev_b64 v[56:57], 12, v[56:57]
	v_lshl_add_u64 v[40:41], v[42:43], 0, v[40:41]
	v_lshl_add_u64 v[50:51], v[42:43], 0, v[50:51]
	v_lshl_add_u64 v[52:53], v[42:43], 0, v[52:53]
	v_lshl_add_u64 v[54:55], v[42:43], 0, v[54:55]
	v_lshl_add_u64 v[56:57], v[42:43], 0, v[56:57]
	global_load_dword v42, v[44:45], off nt
	global_load_dword v43, v[46:47], off nt
	s_nop 0
	global_load_dword v44, v[48:49], off nt
	global_load_dword v45, v[50:51], off nt
	global_load_dword v46, v[52:53], off nt
	global_load_dword v47, v[54:55], off nt
	s_nop 0
	global_load_dword v48, v[56:57], off nt
	s_nop 0
	global_load_dword v40, v[40:41], off nt
	s_waitcnt vmcnt(0)
; __device__ __forceinline__ unsigned pk2(float lo, float hi) { f32v2 v = {lo, hi}; bf16v2 r = __builtin_convertvector(v, bf16v2); return __builtin_bit_cast(unsigned, r); }
; #define LAS __attribute__((address_space(3)))
; #define LDS_WAIT() asm volatile("s_waitcnt lgkmcnt(0)" ::: "memory")
; __device__ __forceinline__ void transpose_item(const float* W, int K, int N, bf16* WT, int k0, int n0, int dst_row0, LAS float* scr, int lane) {
;     ...
; #pragma unroll
;     for (int i = 0; i < 32; ++i) scr[(2 * i + (lane >> 5)) * 33 + (lane & 31)] = wv[i];
;     LDS_WAIT(); asm volatile("" ::: "memory");
;     const int c = lane & 7;
; #pragma unroll
;     for (int j = 0; j < 4; ++j) { const int n = (lane >> 3) + 8 * j; const LAS float* s = scr + (8 * c) * 33 + n;
;         v4u o; o.x = pk2(s[0 * 33], s[1 * 33]); o.y = pk2(s[2 * 33], s[3 * 33]); o.z = pk2(s[4 * 33], s[5 * 33]); o.w = pk2(s[6 * 33], s[7 * 33]);
;         *(v4u*)(WT + (size_t)(dst_row0 + n) * K + k0 + 8 * c) = o; }
;     LDS_WAIT(); asm volatile("" ::: "memory");
	ds_write2_b32 v27, v60, v61 offset1:66
	s_waitcnt vmcnt(28)
	ds_write2_b32 v27, v62, v63 offset0:132 offset1:198
	s_waitcnt vmcnt(26)
	ds_write2_b32 v33, v64, v65 offset0:8 offset1:74
	s_waitcnt vmcnt(24)
	ds_write2_b32 v33, v66, v67 offset0:140 offset1:206
	s_waitcnt vmcnt(22)
	ds_write2_b32 v34, v68, v69 offset0:16 offset1:82
	s_waitcnt vmcnt(20)
	ds_write2_b32 v34, v70, v71 offset0:148 offset1:214
	s_waitcnt vmcnt(18)
	ds_write2_b32 v35, v72, v73 offset0:24 offset1:90
	s_waitcnt vmcnt(16)
	ds_write2_b32 v35, v74, v75 offset0:156 offset1:222
	s_waitcnt vmcnt(14)
	ds_write2_b32 v36, v76, v77 offset0:32 offset1:98
	s_waitcnt vmcnt(12)
	ds_write2_b32 v36, v78, v79 offset0:164 offset1:230
	s_waitcnt vmcnt(10)
	ds_write2_b32 v37, v80, v81 offset0:40 offset1:106
	s_waitcnt vmcnt(8)
	ds_write2_b32 v37, v82, v58 offset0:172 offset1:238
	s_waitcnt vmcnt(6)
	ds_write2_b32 v38, v42, v43 offset0:48 offset1:114
	s_waitcnt vmcnt(4)
	ds_write2_b32 v38, v44, v45 offset0:180 offset1:246
	s_waitcnt vmcnt(2)
	ds_write2_b32 v39, v46, v47 offset0:56 offset1:122
	s_waitcnt vmcnt(0)
	ds_write2_b32 v39, v48, v40 offset0:188 offset1:254
	s_waitcnt lgkmcnt(0)
	ds_read2_b32 v[44:45], v29 offset0:33 offset1:41
	ds_read2_b32 v[46:47], v29 offset1:8
	ds_read2_b32 v[48:49], v29 offset0:66 offset1:74
	ds_read2_b32 v[50:51], v29 offset0:99 offset1:107
	ds_read2_b32 v[52:53], v29 offset0:132 offset1:140
	ds_read2_b32 v[54:55], v29 offset0:165 offset1:173
	ds_read2_b32 v[56:57], v29 offset0:198 offset1:206
	ds_read2_b32 v[58:59], v29 offset0:231 offset1:239
	s_lshl_b32 s94, s5, 1
	s_waitcnt lgkmcnt(6)
	v_cvt_pk_bf16_f32 v40, v46, v44
	v_or_b32_e32 v44, s4, v28
	v_lshl_add_u64 v[60:61], v[22:23], 0, s[94:95]
	v_lshlrev_b32_e32 v62, 10, v44
	v_mov_b32_e32 v63, v179
	s_waitcnt lgkmcnt(4)
	v_cvt_pk_bf16_f32 v41, v48, v50
	s_waitcnt lgkmcnt(2)
	v_cvt_pk_bf16_f32 v42, v52, v54
	s_waitcnt lgkmcnt(0)
	v_cvt_pk_bf16_f32 v43, v56, v58
	v_lshl_add_u64 v[62:63], v[60:61], 0, v[62:63]
	global_store_dwordx4 v[62:63], v[40:43], off sc0 sc1
	v_or_b32_e32 v44, s4, v30
	v_lshlrev_b32_e32 v44, 10, v44
	v_cvt_pk_bf16_f32 v40, v47, v45
	v_cvt_pk_bf16_f32 v41, v49, v51
	v_cvt_pk_bf16_f32 v42, v53, v55
	v_cvt_pk_bf16_f32 v43, v57, v59
	ds_read2_b32 v[46:47], v29 offset0:49 offset1:57
	ds_read2_b32 v[48:49], v29 offset0:16 offset1:24
	ds_read2_b32 v[50:51], v29 offset0:82 offset1:90
	ds_read2_b32 v[52:53], v29 offset0:115 offset1:123
	ds_read2_b32 v[54:55], v29 offset0:148 offset1:156
	ds_read2_b32 v[56:57], v29 offset0:181 offset1:189
	ds_read2_b32 v[58:59], v29 offset0:214 offset1:222
	ds_read2_b32 v[62:63], v29 offset0:247 offset1:255
	v_mov_b32_e32 v45, v179
	v_lshl_add_u64 v[44:45], v[60:61], 0, v[44:45]
	global_store_dwordx4 v[44:45], v[40:43], off sc0 sc1
	v_or_b32_e32 v44, s4, v31
	v_lshlrev_b32_e32 v44, 10, v44
	v_mov_b32_e32 v45, v179
	s_waitcnt lgkmcnt(6)
	v_cvt_pk_bf16_f32 v40, v48, v46
	s_waitcnt lgkmcnt(4)
	v_cvt_pk_bf16_f32 v41, v50, v52
	s_waitcnt lgkmcnt(2)
	v_cvt_pk_bf16_f32 v42, v54, v56
	s_waitcnt lgkmcnt(0)
	v_cvt_pk_bf16_f32 v43, v58, v62
	v_lshl_add_u64 v[44:45], v[60:61], 0, v[44:45]
	global_store_dwordx4 v[44:45], v[40:43], off sc0 sc1
	v_or_b32_e32 v44, s4, v32
	v_lshlrev_b32_e32 v44, 10, v44
	v_mov_b32_e32 v45, v179
	v_cvt_pk_bf16_f32 v40, v49, v47
	v_cvt_pk_bf16_f32 v41, v51, v53
	v_cvt_pk_bf16_f32 v42, v55, v57
	v_cvt_pk_bf16_f32 v43, v59, v63
	v_lshl_add_u64 v[44:45], v[60:61], 0, v[44:45]
	global_store_dwordx4 v[44:45], v[40:43], off sc0 sc1
	s_waitcnt lgkmcnt(0)
